# K loops: priority raised for the load segments instead of the MFMA bursts (loader is the pole); plus saddr DMA, aligned loops, hand-written scan
# baseline (speedup 1.0000x reference)
; #define PG8_STAGE(bufoff, gbase, voff) do { _Pragma("unroll") for (int _i = 0; _i < 2; ++_i) \
;         __builtin_amdgcn_global_load_lds((const unsigned*)((const char*)(gbase) + (voff)[_i]), (PG8_LAS unsigned*)(lds + (bufoff) + ldsw + _i * 8192), 16, 0, 0); } while (0)
; #define PG8_LDA(dst, b, h) do { _Pragma("unroll") for (int m = 0; m < 4; ++m) _Pragma("unroll") for (int k = 0; k < 2; ++k) dst[m][k] = *(const PG8_LAS bf16x8*)(lds + PG8_SA(b, h) + aoff + m * 2048 + k * 1024); } while (0)
; #define PG8_LDB(dst, b, h) do { _Pragma("unroll") for (int n = 0; n < 2; ++n) _Pragma("unroll") for (int k = 0; k < 2; ++k) dst[n][k] = *(const PG8_LAS bf16x8*)(lds + PG8_SB(b, h) + boff + n * 2048 + k * 1024); } while (0)
; #define PG8_MMA(ai, bj, At, Bt) do { __builtin_amdgcn_s_setprio(1); _Pragma("unroll") for (int m = 0; m < 4; ++m) _Pragma("unroll") for (int n = 0; n < 2; ++n) _Pragma("unroll") for (int k = 0; k < 2; ++k) \
;         acc[ai][bj][m][n] = __builtin_amdgcn_mfma_f32_16x16x32_bf16(Bt[n][k], At[m][k], acc[ai][bj][m][n], 0, 0, 0); __builtin_amdgcn_s_setprio(0); } while (0)
; #define PG8_WAIT_V(n) asm volatile("s_waitcnt vmcnt(" #n ")" ::: "memory")
; #define PG8_WAIT_L(n) asm volatile("s_waitcnt lgkmcnt(" #n ")" ::: "memory")
; template <class Epi, class Sched, bool ALIGN_EPI = false, bool SP2 = false>
; __device__ __forceinline__ void gemm_phase(PG8_LAS unsigned char* lds, const Gemm g, const Sched& S, const Epi& E) {
;     ...
;             const bool last = (t == nt - 2);
;             const char* a1 = cA + (size_t)(t + 1) * kstep;
;             const char* a2 = last ? nA : cA + (size_t)(t + 2) * kstep; const char* b2 = last ? nB : cB + (size_t)(t + 2) * kstep;
;             const char* a3 = a2 + kstep; const char* b3 = b2 + kstep;
;             if (last && has_next) S.a_ready(nxt);
;             if constexpr (SP2) {
;             PG8_LDB(B0, 0, 0); PG8_LDB(B1, 0, 1); PG8_SCHED; PG8_LDA(At, 0, 0); PG8_STAGE(PG8_SA(1, 1), a1 + hstep, voffA);
;             PG8_WAIT_V(8); PG8_WAIT_L(0); PG8_BAR; PG8_MMA(0, 0, At, B0); PG8_MMA(0, 1, At, B1); PG8_BAR; PG8_SCHED;
;             PG8_LDA(At, 0, 1); PG8_STAGE(PG8_SB(0, 0), b2, voffB); PG8_STAGE(PG8_SB(0, 1), b2 + hstep, voffB); PG8_STAGE(PG8_SA(0, 0), a2, voffA);
;             PG8_WAIT_V(8); PG8_WAIT_L(0); PG8_BAR; PG8_MMA(1, 0, At, B0); PG8_MMA(1, 1, At, B1); PG8_BAR; PG8_SCHED;
.LBB0_301:
	s_add_u32 s38, s36, 0xfff80080
	s_addc_u32 s39, s37, -1
	s_add_i32 s61, 0, 0x10000
	s_cmp_eq_u32 s60, 28
	s_cselect_b32 s41, s11, s39
	s_cselect_b32 s40, s13, s38
	s_cselect_b32 s39, s56, s59
	s_cselect_b32 s38, s57, s58
	s_add_i32 s64, 0, 0x14000
	v_add_u32_e32 v158, s61, v150
	v_add_u32_e32 v162, s64, v150
	ds_read_b128 v[142:145], v158
	ds_read_b128 v[146:149], v158 offset:1024
	ds_read_b128 v[154:157], v158 offset:2048
	ds_read_b128 v[158:161], v158 offset:3072
	ds_read_b128 v[174:177], v162
	ds_read_b128 v[178:181], v162 offset:1024
	ds_read_b128 v[204:207], v162 offset:2048
	ds_read_b128 v[208:211], v162 offset:3072
	s_add_i32 m0, s47, 0xc000
	ds_read_b128 v[212:215], v153
	ds_read_b128 v[216:219], v153 offset:1024
	ds_read_b128 v[220:223], v153 offset:2048
	ds_read_b128 v[224:227], v153 offset:3072
	ds_read_b128 v[228:231], v153 offset:4096
	ds_read_b128 v[232:235], v153 offset:5120
	ds_read_b128 v[236:239], v153 offset:6144
	ds_read_b128 v[240:243], v153 offset:7168
	global_load_lds_dwordx4 v138, s[36:37]
	s_add_i32 m0, s47, 0xe000
	s_nop 0
	global_load_lds_dwordx4 v140, s[36:37]
	s_waitcnt vmcnt(8)
	s_waitcnt lgkmcnt(0)
	s_barrier
	s_setprio 0
	s_waitcnt lgkmcnt(0)
	v_mfma_f32_16x16x32_bf16 v[128:131], v[142:145], v[212:215], v[128:131]
	v_mfma_f32_16x16x32_bf16 v[120:123], v[154:157], v[212:215], v[120:123]
	v_mfma_f32_16x16x32_bf16 v[112:115], v[142:145], v[220:223], v[112:115]
	v_mfma_f32_16x16x32_bf16 v[104:107], v[154:157], v[220:223], v[104:107]
	v_mfma_f32_16x16x32_bf16 v[96:99], v[142:145], v[228:231], v[96:99]
	v_mfma_f32_16x16x32_bf16 v[88:91], v[154:157], v[228:231], v[88:91]
	v_mfma_f32_16x16x32_bf16 v[80:83], v[142:145], v[236:239], v[80:83]
	v_mfma_f32_16x16x32_bf16 v[72:75], v[154:157], v[236:239], v[72:75]
	v_mfma_f32_16x16x32_bf16 v[128:131], v[146:149], v[216:219], v[128:131]
	v_mfma_f32_16x16x32_bf16 v[120:123], v[158:161], v[216:219], v[120:123]
	v_mfma_f32_16x16x32_bf16 v[112:115], v[146:149], v[224:227], v[112:115]
	v_mfma_f32_16x16x32_bf16 v[104:107], v[158:161], v[224:227], v[104:107]
	v_mfma_f32_16x16x32_bf16 v[96:99], v[146:149], v[232:235], v[96:99]
	v_mfma_f32_16x16x32_bf16 v[88:91], v[158:161], v[232:235], v[88:91]
	v_mfma_f32_16x16x32_bf16 v[80:83], v[146:149], v[240:243], v[80:83]
	v_mfma_f32_16x16x32_bf16 v[72:75], v[158:161], v[240:243], v[72:75]
	s_setprio 1
	s_setprio 0
	v_mfma_f32_16x16x32_bf16 v[124:127], v[174:177], v[212:215], v[124:127]
	v_mfma_f32_16x16x32_bf16 v[116:119], v[204:207], v[212:215], v[116:119]
	v_mfma_f32_16x16x32_bf16 v[108:111], v[174:177], v[220:223], v[108:111]
	v_mfma_f32_16x16x32_bf16 v[100:103], v[204:207], v[220:223], v[100:103]
	v_mfma_f32_16x16x32_bf16 v[92:95], v[174:177], v[228:231], v[92:95]
	v_mfma_f32_16x16x32_bf16 v[84:87], v[204:207], v[228:231], v[84:87]
	v_mfma_f32_16x16x32_bf16 v[76:79], v[174:177], v[236:239], v[76:79]
	v_mfma_f32_16x16x32_bf16 v[68:71], v[204:207], v[236:239], v[68:71]
	v_mfma_f32_16x16x32_bf16 v[124:127], v[178:181], v[216:219], v[124:127]
	v_mfma_f32_16x16x32_bf16 v[116:119], v[208:211], v[216:219], v[116:119]
	v_mfma_f32_16x16x32_bf16 v[108:111], v[178:181], v[224:227], v[108:111]
	v_mfma_f32_16x16x32_bf16 v[100:103], v[208:211], v[224:227], v[100:103]
	v_mfma_f32_16x16x32_bf16 v[92:95], v[178:181], v[232:235], v[92:95]
	v_mfma_f32_16x16x32_bf16 v[84:87], v[208:211], v[232:235], v[84:87]
	v_mfma_f32_16x16x32_bf16 v[76:79], v[178:181], v[240:243], v[76:79]
	v_mfma_f32_16x16x32_bf16 v[68:71], v[208:211], v[240:243], v[68:71]
	s_setprio 1
	s_barrier
	s_add_i32 s61, s61, s42
	s_mov_b32 m0, s61
	ds_read_b128 v[212:215], v153 offset:16384
	ds_read_b128 v[216:219], v153 offset:17408
	ds_read_b128 v[220:223], v153 offset:18432
	ds_read_b128 v[224:227], v153 offset:19456
	ds_read_b128 v[228:231], v153 offset:20480
	ds_read_b128 v[232:235], v153 offset:21504
	ds_read_b128 v[236:239], v153 offset:22528
	ds_read_b128 v[240:243], v153 offset:23552
	global_load_lds_dwordx4 v2, s[38:39]
	s_add_i32 m0, s61, 0x2000
	s_add_u32 s62, s38, 0x80000
	s_addc_u32 s63, s39, 0
	s_add_i32 s61, s64, s42
	global_load_lds_dwordx4 v132, s[38:39]
	s_mov_b32 m0, s61
	s_nop 0
	global_load_lds_dwordx4 v2, s[62:63]
	s_add_i32 m0, s61, 0x2000
	s_nop 0
	global_load_lds_dwordx4 v132, s[62:63]
	s_mov_b32 m0, s47
	s_nop 0
	global_load_lds_dwordx4 v136, s[40:41]
	s_mov_b32 m0, s48
	s_nop 0
	global_load_lds_dwordx4 v134, s[40:41]
	s_waitcnt vmcnt(8)
	s_waitcnt lgkmcnt(0)
	s_barrier
	s_setprio 0
	s_waitcnt lgkmcnt(0)
	v_mfma_f32_16x16x32_bf16 v[64:67], v[142:145], v[212:215], v[64:67]
	v_mfma_f32_16x16x32_bf16 v[56:59], v[154:157], v[212:215], v[56:59]
	v_mfma_f32_16x16x32_bf16 v[48:51], v[142:145], v[220:223], v[48:51]
	v_mfma_f32_16x16x32_bf16 v[40:43], v[154:157], v[220:223], v[40:43]
	v_mfma_f32_16x16x32_bf16 v[32:35], v[142:145], v[228:231], v[32:35]
	v_mfma_f32_16x16x32_bf16 v[24:27], v[154:157], v[228:231], v[24:27]
	v_mfma_f32_16x16x32_bf16 v[16:19], v[142:145], v[236:239], v[16:19]
	v_mfma_f32_16x16x32_bf16 v[8:11], v[154:157], v[236:239], v[8:11]
	v_mfma_f32_16x16x32_bf16 v[64:67], v[146:149], v[216:219], v[64:67]
	v_mfma_f32_16x16x32_bf16 v[56:59], v[158:161], v[216:219], v[56:59]
	v_mfma_f32_16x16x32_bf16 v[48:51], v[146:149], v[224:227], v[48:51]
	v_mfma_f32_16x16x32_bf16 v[40:43], v[158:161], v[224:227], v[40:43]
	v_mfma_f32_16x16x32_bf16 v[32:35], v[146:149], v[232:235], v[32:35]
	v_mfma_f32_16x16x32_bf16 v[24:27], v[158:161], v[232:235], v[24:27]
	v_mfma_f32_16x16x32_bf16 v[16:19], v[146:149], v[240:243], v[16:19]
	v_mfma_f32_16x16x32_bf16 v[8:11], v[158:161], v[240:243], v[8:11]
	s_setprio 1
	s_setprio 0
	v_mfma_f32_16x16x32_bf16 v[60:63], v[174:177], v[212:215], v[60:63]
	v_mfma_f32_16x16x32_bf16 v[52:55], v[204:207], v[212:215], v[52:55]
	v_mfma_f32_16x16x32_bf16 v[44:47], v[174:177], v[220:223], v[44:47]
	v_mfma_f32_16x16x32_bf16 v[36:39], v[204:207], v[220:223], v[36:39]
	v_mfma_f32_16x16x32_bf16 v[28:31], v[174:177], v[228:231], v[28:31]
	v_mfma_f32_16x16x32_bf16 v[20:23], v[204:207], v[228:231], v[20:23]
	v_mfma_f32_16x16x32_bf16 v[12:15], v[174:177], v[236:239], v[12:15]
	v_mfma_f32_16x16x32_bf16 v[4:7], v[204:207], v[236:239], v[4:7]
	v_mfma_f32_16x16x32_bf16 v[60:63], v[178:181], v[216:219], v[60:63]
	v_mfma_f32_16x16x32_bf16 v[52:55], v[208:211], v[216:219], v[52:55]
	v_mfma_f32_16x16x32_bf16 v[44:47], v[178:181], v[224:227], v[44:47]
	v_mfma_f32_16x16x32_bf16 v[36:39], v[208:211], v[224:227], v[36:39]
	v_mfma_f32_16x16x32_bf16 v[28:31], v[178:181], v[232:235], v[28:31]
	v_mfma_f32_16x16x32_bf16 v[20:23], v[208:211], v[232:235], v[20:23]
	v_mfma_f32_16x16x32_bf16 v[12:15], v[178:181], v[240:243], v[12:15]
	v_mfma_f32_16x16x32_bf16 v[4:7], v[208:211], v[240:243], v[4:7]
	s_setprio 1
	s_barrier
; #define PG8_STAGE(bufoff, gbase, voff) do { _Pragma("unroll") for (int _i = 0; _i < 2; ++_i) \
;         __builtin_amdgcn_global_load_lds((const unsigned*)((const char*)(gbase) + (voff)[_i]), (PG8_LAS unsigned*)(lds + (bufoff) + ldsw + _i * 8192), 16, 0, 0); } while (0)
; #define PG8_LDA(dst, b, h) do { _Pragma("unroll") for (int m = 0; m < 4; ++m) _Pragma("unroll") for (int k = 0; k < 2; ++k) dst[m][k] = *(const PG8_LAS bf16x8*)(lds + PG8_SA(b, h) + aoff + m * 2048 + k * 1024); } while (0)
; #define PG8_LDB(dst, b, h) do { _Pragma("unroll") for (int n = 0; n < 2; ++n) _Pragma("unroll") for (int k = 0; k < 2; ++k) dst[n][k] = *(const PG8_LAS bf16x8*)(lds + PG8_SB(b, h) + boff + n * 2048 + k * 1024); } while (0)
; #define PG8_MMA(ai, bj, At, Bt) do { __builtin_amdgcn_s_setprio(1); _Pragma("unroll") for (int m = 0; m < 4; ++m) _Pragma("unroll") for (int n = 0; n < 2; ++n) _Pragma("unroll") for (int k = 0; k < 2; ++k) \
;         acc[ai][bj][m][n] = __builtin_amdgcn_mfma_f32_16x16x32_bf16(Bt[n][k], At[m][k], acc[ai][bj][m][n], 0, 0, 0); __builtin_amdgcn_s_setprio(0); } while (0)
; #define PG8_WAIT_V(n) asm volatile("s_waitcnt vmcnt(" #n ")" ::: "memory")
; #define PG8_WAIT_L(n) asm volatile("s_waitcnt lgkmcnt(" #n ")" ::: "memory")
; #define PG8_BAR __builtin_amdgcn_s_barrier()
; #define PG8_SCHED __builtin_amdgcn_sched_barrier(0)
; template <class Epi, class Sched, bool ALIGN_EPI = false, bool SP2 = false>
; __device__ __forceinline__ void gemm_phase(PG8_LAS unsigned char* lds, const Gemm g, const Sched& S, const Epi& E) {
;     ...
;             PG8_LDB(B0, 1, 0); PG8_LDB(B1, 1, 1); PG8_SCHED; PG8_LDA(At, 1, 0); PG8_STAGE(PG8_SA(0, 1), a2 + hstep, voffA);
;             PG8_WAIT_V(8); PG8_WAIT_L(0); PG8_BAR; PG8_MMA(0, 0, At, B0); PG8_MMA(0, 1, At, B1); PG8_BAR; PG8_SCHED;
;             PG8_LDA(At, 1, 1); PG8_STAGE(PG8_SB(1, 0), b3, voffB); PG8_STAGE(PG8_SB(1, 1), b3 + hstep, voffB); PG8_STAGE(PG8_SA(1, 0), a3, voffA);
;             PG8_WAIT_V(8); PG8_WAIT_L(0); PG8_BAR; PG8_MMA(1, 0, At, B0); PG8_MMA(1, 1, At, B1); PG8_BAR; PG8_SCHED;
	s_add_i32 s61, 0, 0x18000
	s_add_i32 s62, 0, 0x1c000
	v_add_u32_e32 v158, s61, v150
	v_add_u32_e32 v164, s62, v150
	ds_read_b128 v[142:145], v158
	ds_read_b128 v[146:149], v158 offset:1024
	ds_read_b128 v[154:157], v158 offset:2048
	ds_read_b128 v[158:161], v158 offset:3072
	ds_read_b128 v[174:177], v164
	ds_read_b128 v[178:181], v164 offset:1024
	ds_read_b128 v[204:207], v164 offset:2048
	ds_read_b128 v[208:211], v164 offset:3072
	s_add_u32 s100, s40, 0x80
	s_addc_u32 s101, s41, 0
	s_add_u32 s40, s40, 0x80000
	s_addc_u32 s41, s41, 0
	s_mov_b32 m0, s49
	ds_read_b128 v[212:215], v153 offset:32768
	ds_read_b128 v[216:219], v153 offset:33792
	ds_read_b128 v[220:223], v153 offset:34816
	ds_read_b128 v[224:227], v153 offset:35840
	ds_read_b128 v[228:231], v153 offset:36864
	ds_read_b128 v[232:235], v153 offset:37888
	ds_read_b128 v[236:239], v153 offset:38912
	ds_read_b128 v[240:243], v153 offset:39936
	global_load_lds_dwordx4 v136, s[40:41]
	s_mov_b32 m0, s50
	s_nop 0
	global_load_lds_dwordx4 v134, s[40:41]
	s_waitcnt vmcnt(8)
	s_waitcnt lgkmcnt(0)
	s_barrier
	s_setprio 0
	s_waitcnt lgkmcnt(0)
	v_mfma_f32_16x16x32_bf16 v[128:131], v[142:145], v[212:215], v[128:131]
	v_mfma_f32_16x16x32_bf16 v[120:123], v[154:157], v[212:215], v[120:123]
	v_mfma_f32_16x16x32_bf16 v[112:115], v[142:145], v[220:223], v[112:115]
	v_mfma_f32_16x16x32_bf16 v[104:107], v[154:157], v[220:223], v[104:107]
	v_mfma_f32_16x16x32_bf16 v[96:99], v[142:145], v[228:231], v[96:99]
	v_mfma_f32_16x16x32_bf16 v[88:91], v[154:157], v[228:231], v[88:91]
	v_mfma_f32_16x16x32_bf16 v[80:83], v[142:145], v[236:239], v[80:83]
	v_mfma_f32_16x16x32_bf16 v[72:75], v[154:157], v[236:239], v[72:75]
	v_mfma_f32_16x16x32_bf16 v[128:131], v[146:149], v[216:219], v[128:131]
	v_mfma_f32_16x16x32_bf16 v[120:123], v[158:161], v[216:219], v[120:123]
	v_mfma_f32_16x16x32_bf16 v[112:115], v[146:149], v[224:227], v[112:115]
	v_mfma_f32_16x16x32_bf16 v[104:107], v[158:161], v[224:227], v[104:107]
	v_mfma_f32_16x16x32_bf16 v[96:99], v[146:149], v[232:235], v[96:99]
	v_mfma_f32_16x16x32_bf16 v[88:91], v[158:161], v[232:235], v[88:91]
	v_mfma_f32_16x16x32_bf16 v[80:83], v[146:149], v[240:243], v[80:83]
	v_mfma_f32_16x16x32_bf16 v[72:75], v[158:161], v[240:243], v[72:75]
	s_setprio 1
	s_setprio 0
	v_mfma_f32_16x16x32_bf16 v[124:127], v[174:177], v[212:215], v[124:127]
	v_mfma_f32_16x16x32_bf16 v[116:119], v[204:207], v[212:215], v[116:119]
	v_mfma_f32_16x16x32_bf16 v[108:111], v[174:177], v[220:223], v[108:111]
	v_mfma_f32_16x16x32_bf16 v[100:103], v[204:207], v[220:223], v[100:103]
	v_mfma_f32_16x16x32_bf16 v[92:95], v[174:177], v[228:231], v[92:95]
	v_mfma_f32_16x16x32_bf16 v[84:87], v[204:207], v[228:231], v[84:87]
	v_mfma_f32_16x16x32_bf16 v[76:79], v[174:177], v[236:239], v[76:79]
	v_mfma_f32_16x16x32_bf16 v[68:71], v[204:207], v[236:239], v[68:71]
	v_mfma_f32_16x16x32_bf16 v[124:127], v[178:181], v[216:219], v[124:127]
	v_mfma_f32_16x16x32_bf16 v[116:119], v[208:211], v[216:219], v[116:119]
	v_mfma_f32_16x16x32_bf16 v[108:111], v[178:181], v[224:227], v[108:111]
	v_mfma_f32_16x16x32_bf16 v[100:103], v[208:211], v[224:227], v[100:103]
	v_mfma_f32_16x16x32_bf16 v[92:95], v[178:181], v[232:235], v[92:95]
	v_mfma_f32_16x16x32_bf16 v[84:87], v[208:211], v[232:235], v[84:87]
	v_mfma_f32_16x16x32_bf16 v[76:79], v[178:181], v[240:243], v[76:79]
	v_mfma_f32_16x16x32_bf16 v[68:71], v[208:211], v[240:243], v[68:71]
	s_setprio 1
	s_barrier
	s_add_i32 s40, s61, s42
	s_add_i32 m0, s40, 0xffffff80
	ds_read_b128 v[212:215], v153 offset:49152
	ds_read_b128 v[216:219], v153 offset:50176
	ds_read_b128 v[220:223], v153 offset:51200
	ds_read_b128 v[224:227], v153 offset:52224
	ds_read_b128 v[228:231], v153 offset:53248
	ds_read_b128 v[232:235], v153 offset:54272
	ds_read_b128 v[236:239], v153 offset:55296
	ds_read_b128 v[240:243], v153 offset:56320
	global_load_lds_dwordx4 v2, s[38:39] offset:128
	s_add_i32 m0, s40, 0x1f80
	s_add_i32 s40, s62, s42
	global_load_lds_dwordx4 v132, s[38:39] offset:128
	s_add_u32 s38, s38, 0x80080
	s_addc_u32 s39, s39, 0
	s_mov_b32 m0, s40
	s_nop 0
	global_load_lds_dwordx4 v2, s[38:39]
	s_add_i32 m0, s40, 0x2000
	s_nop 0
	global_load_lds_dwordx4 v132, s[38:39]
	s_mov_b32 m0, s51
	s_nop 0
	global_load_lds_dwordx4 v136, s[100:101]
	s_mov_b32 m0, s53
	s_nop 0
	global_load_lds_dwordx4 v134, s[100:101]
	s_nop 0
	s_waitcnt vmcnt(8)
	s_waitcnt lgkmcnt(0)
	s_barrier
	s_setprio 0
	s_waitcnt lgkmcnt(0)
	v_mfma_f32_16x16x32_bf16 v[64:67], v[142:145], v[212:215], v[64:67]
	v_mfma_f32_16x16x32_bf16 v[56:59], v[154:157], v[212:215], v[56:59]
	v_mfma_f32_16x16x32_bf16 v[48:51], v[142:145], v[220:223], v[48:51]
	v_mfma_f32_16x16x32_bf16 v[40:43], v[154:157], v[220:223], v[40:43]
	v_mfma_f32_16x16x32_bf16 v[32:35], v[142:145], v[228:231], v[32:35]
	v_mfma_f32_16x16x32_bf16 v[24:27], v[154:157], v[228:231], v[24:27]
	v_mfma_f32_16x16x32_bf16 v[16:19], v[142:145], v[236:239], v[16:19]
	v_mfma_f32_16x16x32_bf16 v[8:11], v[154:157], v[236:239], v[8:11]
	v_mfma_f32_16x16x32_bf16 v[64:67], v[146:149], v[216:219], v[64:67]
	v_mfma_f32_16x16x32_bf16 v[56:59], v[158:161], v[216:219], v[56:59]
	v_mfma_f32_16x16x32_bf16 v[48:51], v[146:149], v[224:227], v[48:51]
	v_mfma_f32_16x16x32_bf16 v[40:43], v[158:161], v[224:227], v[40:43]
	v_mfma_f32_16x16x32_bf16 v[32:35], v[146:149], v[232:235], v[32:35]
	v_mfma_f32_16x16x32_bf16 v[24:27], v[158:161], v[232:235], v[24:27]
	v_mfma_f32_16x16x32_bf16 v[16:19], v[146:149], v[240:243], v[16:19]
	v_mfma_f32_16x16x32_bf16 v[8:11], v[158:161], v[240:243], v[8:11]
	s_setprio 1
	s_setprio 0
	v_mfma_f32_16x16x32_bf16 v[60:63], v[174:177], v[212:215], v[60:63]
	v_mfma_f32_16x16x32_bf16 v[52:55], v[204:207], v[212:215], v[52:55]
	v_mfma_f32_16x16x32_bf16 v[44:47], v[174:177], v[220:223], v[44:47]
	v_mfma_f32_16x16x32_bf16 v[36:39], v[204:207], v[220:223], v[36:39]
	v_mfma_f32_16x16x32_bf16 v[28:31], v[174:177], v[228:231], v[28:31]
	v_mfma_f32_16x16x32_bf16 v[20:23], v[204:207], v[228:231], v[20:23]
	v_mfma_f32_16x16x32_bf16 v[12:15], v[174:177], v[236:239], v[12:15]
	v_mfma_f32_16x16x32_bf16 v[4:7], v[204:207], v[236:239], v[4:7]
	v_mfma_f32_16x16x32_bf16 v[60:63], v[178:181], v[216:219], v[60:63]
	v_mfma_f32_16x16x32_bf16 v[52:55], v[208:211], v[216:219], v[52:55]
	v_mfma_f32_16x16x32_bf16 v[44:47], v[178:181], v[224:227], v[44:47]
	v_mfma_f32_16x16x32_bf16 v[36:39], v[208:211], v[224:227], v[36:39]
	v_mfma_f32_16x16x32_bf16 v[28:31], v[178:181], v[232:235], v[28:31]
	v_mfma_f32_16x16x32_bf16 v[20:23], v[208:211], v[232:235], v[20:23]
	v_mfma_f32_16x16x32_bf16 v[12:15], v[178:181], v[240:243], v[12:15]
	v_mfma_f32_16x16x32_bf16 v[4:7], v[208:211], v[240:243], v[4:7]
	s_setprio 1
	s_barrier
	s_add_i32 s60, s60, 2
	s_add_u32 s36, s36, 0x100
	s_addc_u32 s37, s37, 0
	s_add_u32 s58, s58, 0x100
	s_addc_u32 s59, s59, 0
	s_cmp_gt_u32 s60, 29
	s_cbranch_scc0 .LBB0_301
	s_and_b64 vcc, exec, s[8:9]
	s_cbranch_vccz .LBB0_304
	s_barrier

; #define PG8_STAGE(bufoff, gbase, voff) do { _Pragma("unroll") for (int _i = 0; _i < 2; ++_i) \
;         __builtin_amdgcn_global_load_lds((const unsigned*)((const char*)(gbase) + (voff)[_i]), (PG8_LAS unsigned*)(lds + (bufoff) + ldsw + _i * 8192), 16, 0, 0); } while (0)
; #define PG8_LDA(dst, b, h) do { _Pragma("unroll") for (int m = 0; m < 4; ++m) _Pragma("unroll") for (int k = 0; k < 2; ++k) dst[m][k] = *(const PG8_LAS bf16x8*)(lds + PG8_SA(b, h) + aoff + m * 2048 + k * 1024); } while (0)
; #define PG8_LDB(dst, b, h) do { _Pragma("unroll") for (int n = 0; n < 2; ++n) _Pragma("unroll") for (int k = 0; k < 2; ++k) dst[n][k] = *(const PG8_LAS bf16x8*)(lds + PG8_SB(b, h) + boff + n * 2048 + k * 1024); } while (0)
; #define PG8_MMA(ai, bj, At, Bt) do { __builtin_amdgcn_s_setprio(1); _Pragma("unroll") for (int m = 0; m < 4; ++m) _Pragma("unroll") for (int n = 0; n < 2; ++n) _Pragma("unroll") for (int k = 0; k < 2; ++k) \
;         acc[ai][bj][m][n] = __builtin_amdgcn_mfma_f32_16x16x32_bf16(Bt[n][k], At[m][k], acc[ai][bj][m][n], 0, 0, 0); __builtin_amdgcn_s_setprio(0); } while (0)
; #define PG8_WAIT_V(n) asm volatile("s_waitcnt vmcnt(" #n ")" ::: "memory")
; #define PG8_WAIT_L(n) asm volatile("s_waitcnt lgkmcnt(" #n ")" ::: "memory")
; template <class Epi, class Sched, bool ALIGN_EPI = false, bool SP2 = false>
; __device__ __forceinline__ void gemm_phase(PG8_LAS unsigned char* lds, const Gemm g, const Sched& S, const Epi& E) {
;     ...
;             const bool last = (t == nt - 2);
;             const char* a1 = cA + (size_t)(t + 1) * kstep;
;             const char* a2 = last ? nA : cA + (size_t)(t + 2) * kstep; const char* b2 = last ? nB : cB + (size_t)(t + 2) * kstep;
;             const char* a3 = a2 + kstep; const char* b3 = b2 + kstep;
;             if (last && has_next) S.a_ready(nxt);
;             if constexpr (SP2) {
;             PG8_LDB(B0, 0, 0); PG8_LDB(B1, 0, 1); PG8_SCHED; PG8_LDA(At, 0, 0); PG8_STAGE(PG8_SA(1, 1), a1 + hstep, voffA);
;             PG8_WAIT_V(8); PG8_WAIT_L(0); PG8_BAR; PG8_MMA(0, 0, At, B0); PG8_MMA(0, 1, At, B1); PG8_BAR; PG8_SCHED;
;             PG8_LDA(At, 0, 1); PG8_STAGE(PG8_SB(0, 0), b2, voffB); PG8_STAGE(PG8_SB(0, 1), b2 + hstep, voffB); PG8_STAGE(PG8_SA(0, 0), a2, voffA);
;             PG8_WAIT_V(8); PG8_WAIT_L(0); PG8_BAR; PG8_MMA(1, 0, At, B0); PG8_MMA(1, 1, At, B1); PG8_BAR; PG8_SCHED;
.LBB0_575:
	s_add_u32 s36, s34, 0x100
	s_addc_u32 s37, s35, 0
	s_add_i32 s64, 0, 0x10000
	s_cmpk_eq_i32 s63, 0x52
	s_cselect_b32 s41, s5, s37
	s_cselect_b32 s40, s4, s36
	v_add_u32_e32 v135, s64, v173
	s_cselect_b32 s39, s31, s62
	s_cselect_b32 s38, s30, s61
	s_add_i32 s65, 0, 0x14000
	ds_read_b128 v[142:145], v135
	ds_read_b128 v[146:149], v135 offset:1024
	ds_read_b128 v[150:153], v135 offset:2048
	ds_read_b128 v[154:157], v135 offset:3072
	v_add_u32_e32 v135, s65, v173
	ds_read_b128 v[158:161], v135
	ds_read_b128 v[174:177], v135 offset:1024
	ds_read_b128 v[180:183], v135 offset:2048
	ds_read_b128 v[204:207], v135 offset:3072
	v_lshl_add_u64 v[162:163], s[34:35], 0, v[138:139]
	s_add_i32 m0, s47, 0xc000
	ds_read_b128 v[208:211], v179
	ds_read_b128 v[212:215], v179 offset:1024
	ds_read_b128 v[216:219], v179 offset:2048
	ds_read_b128 v[220:223], v179 offset:3072
	ds_read_b128 v[224:227], v179 offset:4096
	ds_read_b128 v[228:231], v179 offset:5120
	ds_read_b128 v[232:235], v179 offset:6144
	ds_read_b128 v[236:239], v179 offset:7168
	global_load_lds_dwordx4 v[162:163], off
	v_lshl_add_u64 v[162:163], s[34:35], 0, v[140:141]
	s_add_i32 m0, s47, 0xe000
	s_nop 0
	global_load_lds_dwordx4 v[162:163], off
	s_waitcnt vmcnt(8)
	s_waitcnt lgkmcnt(0)
	s_barrier
	s_setprio 0
	s_waitcnt lgkmcnt(0)
	v_mfma_f32_16x16x32_bf16 v[128:131], v[142:145], v[208:211], v[128:131]
	v_mfma_f32_16x16x32_bf16 v[124:127], v[150:153], v[208:211], v[124:127]
	v_mfma_f32_16x16x32_bf16 v[112:115], v[142:145], v[216:219], v[112:115]
	v_mfma_f32_16x16x32_bf16 v[108:111], v[150:153], v[216:219], v[108:111]
	v_mfma_f32_16x16x32_bf16 v[96:99], v[142:145], v[224:227], v[96:99]
	v_mfma_f32_16x16x32_bf16 v[92:95], v[150:153], v[224:227], v[92:95]
	v_mfma_f32_16x16x32_bf16 v[80:83], v[142:145], v[232:235], v[80:83]
	v_mfma_f32_16x16x32_bf16 v[76:79], v[150:153], v[232:235], v[76:79]
	v_mfma_f32_16x16x32_bf16 v[128:131], v[146:149], v[212:215], v[128:131]
	v_mfma_f32_16x16x32_bf16 v[124:127], v[154:157], v[212:215], v[124:127]
	v_mfma_f32_16x16x32_bf16 v[112:115], v[146:149], v[220:223], v[112:115]
	v_mfma_f32_16x16x32_bf16 v[108:111], v[154:157], v[220:223], v[108:111]
	v_mfma_f32_16x16x32_bf16 v[96:99], v[146:149], v[228:231], v[96:99]
	v_mfma_f32_16x16x32_bf16 v[92:95], v[154:157], v[228:231], v[92:95]
	v_mfma_f32_16x16x32_bf16 v[80:83], v[146:149], v[236:239], v[80:83]
	v_mfma_f32_16x16x32_bf16 v[76:79], v[154:157], v[236:239], v[76:79]
	s_setprio 1
	s_setprio 0
	v_mfma_f32_16x16x32_bf16 v[120:123], v[158:161], v[208:211], v[120:123]
	v_mfma_f32_16x16x32_bf16 v[116:119], v[180:183], v[208:211], v[116:119]
	v_mfma_f32_16x16x32_bf16 v[104:107], v[158:161], v[216:219], v[104:107]
	v_mfma_f32_16x16x32_bf16 v[100:103], v[180:183], v[216:219], v[100:103]
	v_mfma_f32_16x16x32_bf16 v[88:91], v[158:161], v[224:227], v[88:91]
	v_mfma_f32_16x16x32_bf16 v[84:87], v[180:183], v[224:227], v[84:87]
	v_mfma_f32_16x16x32_bf16 v[72:75], v[158:161], v[232:235], v[72:75]
	v_mfma_f32_16x16x32_bf16 v[68:71], v[180:183], v[232:235], v[68:71]
	v_mfma_f32_16x16x32_bf16 v[120:123], v[174:177], v[212:215], v[120:123]
	v_mfma_f32_16x16x32_bf16 v[116:119], v[204:207], v[212:215], v[116:119]
	v_mfma_f32_16x16x32_bf16 v[104:107], v[174:177], v[220:223], v[104:107]
	v_mfma_f32_16x16x32_bf16 v[100:103], v[204:207], v[220:223], v[100:103]
	v_mfma_f32_16x16x32_bf16 v[88:91], v[174:177], v[228:231], v[88:91]
	v_mfma_f32_16x16x32_bf16 v[84:87], v[204:207], v[228:231], v[84:87]
	v_mfma_f32_16x16x32_bf16 v[72:75], v[174:177], v[236:239], v[72:75]
	v_mfma_f32_16x16x32_bf16 v[68:71], v[204:207], v[236:239], v[68:71]
	s_setprio 1
	s_barrier
	s_add_i32 s34, s64, s46
	s_mov_b32 m0, s34
	ds_read_b128 v[208:211], v179 offset:16384
	ds_read_b128 v[212:215], v179 offset:17408
	ds_read_b128 v[216:219], v179 offset:18432
	ds_read_b128 v[220:223], v179 offset:19456
	ds_read_b128 v[224:227], v179 offset:20480
	ds_read_b128 v[228:231], v179 offset:21504
	ds_read_b128 v[232:235], v179 offset:22528
	ds_read_b128 v[236:239], v179 offset:23552
	global_load_lds_dwordx4 v2, s[38:39]
	s_add_i32 m0, s34, 0x2000
	s_add_u32 s34, s38, 0x158000
	s_addc_u32 s35, s39, 0
	s_add_i32 s64, s65, s46
	global_load_lds_dwordx4 v132, s[38:39]
	s_mov_b32 m0, s64
	s_nop 0
	global_load_lds_dwordx4 v2, s[34:35]
	s_add_i32 m0, s64, 0x2000
	s_nop 0
	global_load_lds_dwordx4 v132, s[34:35]
	s_mov_b32 m0, s47
	s_nop 0
	global_load_lds_dwordx4 v2, s[40:41]
	s_mov_b32 m0, s48
	s_nop 0
	global_load_lds_dwordx4 v132, s[40:41]
	s_waitcnt vmcnt(8)
	s_waitcnt lgkmcnt(0)
	s_barrier
; #define PG8_STAGE(bufoff, gbase, voff) do { _Pragma("unroll") for (int _i = 0; _i < 2; ++_i) \
;         __builtin_amdgcn_global_load_lds((const unsigned*)((const char*)(gbase) + (voff)[_i]), (PG8_LAS unsigned*)(lds + (bufoff) + ldsw + _i * 8192), 16, 0, 0); } while (0)
; #define PG8_LDA(dst, b, h) do { _Pragma("unroll") for (int m = 0; m < 4; ++m) _Pragma("unroll") for (int k = 0; k < 2; ++k) dst[m][k] = *(const PG8_LAS bf16x8*)(lds + PG8_SA(b, h) + aoff + m * 2048 + k * 1024); } while (0)
; #define PG8_LDB(dst, b, h) do { _Pragma("unroll") for (int n = 0; n < 2; ++n) _Pragma("unroll") for (int k = 0; k < 2; ++k) dst[n][k] = *(const PG8_LAS bf16x8*)(lds + PG8_SB(b, h) + boff + n * 2048 + k * 1024); } while (0)
; #define PG8_MMA(ai, bj, At, Bt) do { __builtin_amdgcn_s_setprio(1); _Pragma("unroll") for (int m = 0; m < 4; ++m) _Pragma("unroll") for (int n = 0; n < 2; ++n) _Pragma("unroll") for (int k = 0; k < 2; ++k) \
;         acc[ai][bj][m][n] = __builtin_amdgcn_mfma_f32_16x16x32_bf16(Bt[n][k], At[m][k], acc[ai][bj][m][n], 0, 0, 0); __builtin_amdgcn_s_setprio(0); } while (0)
; #define PG8_WAIT_V(n) asm volatile("s_waitcnt vmcnt(" #n ")" ::: "memory")
; #define PG8_WAIT_L(n) asm volatile("s_waitcnt lgkmcnt(" #n ")" ::: "memory")
; #define PG8_BAR __builtin_amdgcn_s_barrier()
; #define PG8_SCHED __builtin_amdgcn_sched_barrier(0)
; template <class Epi, class Sched, bool ALIGN_EPI = false, bool SP2 = false>
; __device__ __forceinline__ void gemm_phase(PG8_LAS unsigned char* lds, const Gemm g, const Sched& S, const Epi& E) {
;     ...
;             PG8_WAIT_V(8); PG8_WAIT_L(0); PG8_BAR; PG8_MMA(1, 0, At, B0); PG8_MMA(1, 1, At, B1); PG8_BAR; PG8_SCHED;
;             PG8_LDB(B0, 1, 0); PG8_LDB(B1, 1, 1); PG8_SCHED; PG8_LDA(At, 1, 0); PG8_STAGE(PG8_SA(0, 1), a2 + hstep, voffA);
;             PG8_WAIT_V(8); PG8_WAIT_L(0); PG8_BAR; PG8_MMA(0, 0, At, B0); PG8_MMA(0, 1, At, B1); PG8_BAR; PG8_SCHED;
	s_setprio 0
	s_waitcnt lgkmcnt(0)
	v_mfma_f32_16x16x32_bf16 v[64:67], v[142:145], v[208:211], v[64:67]
	v_mfma_f32_16x16x32_bf16 v[60:63], v[150:153], v[208:211], v[60:63]
	v_mfma_f32_16x16x32_bf16 v[48:51], v[142:145], v[216:219], v[48:51]
	v_mfma_f32_16x16x32_bf16 v[44:47], v[150:153], v[216:219], v[44:47]
	v_mfma_f32_16x16x32_bf16 v[32:35], v[142:145], v[224:227], v[32:35]
	v_mfma_f32_16x16x32_bf16 v[28:31], v[150:153], v[224:227], v[28:31]
	v_mfma_f32_16x16x32_bf16 v[16:19], v[142:145], v[232:235], v[16:19]
	v_mfma_f32_16x16x32_bf16 v[12:15], v[150:153], v[232:235], v[12:15]
	v_mfma_f32_16x16x32_bf16 v[64:67], v[146:149], v[212:215], v[64:67]
	v_mfma_f32_16x16x32_bf16 v[60:63], v[154:157], v[212:215], v[60:63]
	v_mfma_f32_16x16x32_bf16 v[48:51], v[146:149], v[220:223], v[48:51]
	v_mfma_f32_16x16x32_bf16 v[44:47], v[154:157], v[220:223], v[44:47]
	v_mfma_f32_16x16x32_bf16 v[32:35], v[146:149], v[228:231], v[32:35]
	v_mfma_f32_16x16x32_bf16 v[28:31], v[154:157], v[228:231], v[28:31]
	v_mfma_f32_16x16x32_bf16 v[16:19], v[146:149], v[236:239], v[16:19]
	v_mfma_f32_16x16x32_bf16 v[12:15], v[154:157], v[236:239], v[12:15]
	s_setprio 1
	s_setprio 0
	v_mfma_f32_16x16x32_bf16 v[56:59], v[158:161], v[208:211], v[56:59]
	v_mfma_f32_16x16x32_bf16 v[52:55], v[180:183], v[208:211], v[52:55]
	v_mfma_f32_16x16x32_bf16 v[40:43], v[158:161], v[216:219], v[40:43]
	v_mfma_f32_16x16x32_bf16 v[36:39], v[180:183], v[216:219], v[36:39]
	v_mfma_f32_16x16x32_bf16 v[24:27], v[158:161], v[224:227], v[24:27]
	v_mfma_f32_16x16x32_bf16 v[20:23], v[180:183], v[224:227], v[20:23]
	v_mfma_f32_16x16x32_bf16 v[8:11], v[158:161], v[232:235], v[8:11]
	v_mfma_f32_16x16x32_bf16 v[4:7], v[180:183], v[232:235], v[4:7]
	v_mfma_f32_16x16x32_bf16 v[56:59], v[174:177], v[212:215], v[56:59]
	v_mfma_f32_16x16x32_bf16 v[52:55], v[204:207], v[212:215], v[52:55]
	v_mfma_f32_16x16x32_bf16 v[40:43], v[174:177], v[220:223], v[40:43]
	v_mfma_f32_16x16x32_bf16 v[36:39], v[204:207], v[220:223], v[36:39]
	v_mfma_f32_16x16x32_bf16 v[24:27], v[174:177], v[228:231], v[24:27]
	v_mfma_f32_16x16x32_bf16 v[20:23], v[204:207], v[228:231], v[20:23]
	v_mfma_f32_16x16x32_bf16 v[8:11], v[174:177], v[236:239], v[8:11]
	v_mfma_f32_16x16x32_bf16 v[4:7], v[204:207], v[236:239], v[4:7]
	s_setprio 1
	s_barrier
	s_add_i32 s64, 0, 0x18000
	v_add_u32_e32 v135, s64, v173
	s_add_i32 s65, 0, 0x1c000
	ds_read_b128 v[142:145], v135
	ds_read_b128 v[146:149], v135 offset:1024
	ds_read_b128 v[150:153], v135 offset:2048
	ds_read_b128 v[154:157], v135 offset:3072
	v_add_u32_e32 v135, s65, v173
	ds_read_b128 v[158:161], v135
	ds_read_b128 v[174:177], v135 offset:1024
	ds_read_b128 v[180:183], v135 offset:2048
	ds_read_b128 v[204:207], v135 offset:3072
	s_add_u32 s34, s40, 0x158000
	s_addc_u32 s35, s41, 0
	s_mov_b32 m0, s49
	ds_read_b128 v[208:211], v179 offset:32768
	ds_read_b128 v[212:215], v179 offset:33792
	ds_read_b128 v[216:219], v179 offset:34816
	ds_read_b128 v[220:223], v179 offset:35840
	ds_read_b128 v[224:227], v179 offset:36864
	ds_read_b128 v[228:231], v179 offset:37888
	ds_read_b128 v[232:235], v179 offset:38912
	ds_read_b128 v[236:239], v179 offset:39936
	global_load_lds_dwordx4 v2, s[34:35]
	s_mov_b32 m0, s50
	s_nop 0
	global_load_lds_dwordx4 v132, s[34:35]
	s_nop 0
	s_waitcnt vmcnt(8)
	s_waitcnt lgkmcnt(0)
	s_barrier
	s_setprio 0
	s_waitcnt lgkmcnt(0)
	v_mfma_f32_16x16x32_bf16 v[128:131], v[142:145], v[208:211], v[128:131]
	v_mfma_f32_16x16x32_bf16 v[124:127], v[150:153], v[208:211], v[124:127]
	v_mfma_f32_16x16x32_bf16 v[112:115], v[142:145], v[216:219], v[112:115]
	v_mfma_f32_16x16x32_bf16 v[108:111], v[150:153], v[216:219], v[108:111]
	v_mfma_f32_16x16x32_bf16 v[96:99], v[142:145], v[224:227], v[96:99]
	v_mfma_f32_16x16x32_bf16 v[92:95], v[150:153], v[224:227], v[92:95]
	v_mfma_f32_16x16x32_bf16 v[80:83], v[142:145], v[232:235], v[80:83]
	v_mfma_f32_16x16x32_bf16 v[76:79], v[150:153], v[232:235], v[76:79]
	v_mfma_f32_16x16x32_bf16 v[128:131], v[146:149], v[212:215], v[128:131]
	v_mfma_f32_16x16x32_bf16 v[124:127], v[154:157], v[212:215], v[124:127]
	v_mfma_f32_16x16x32_bf16 v[112:115], v[146:149], v[220:223], v[112:115]
	v_mfma_f32_16x16x32_bf16 v[108:111], v[154:157], v[220:223], v[108:111]
	v_mfma_f32_16x16x32_bf16 v[96:99], v[146:149], v[228:231], v[96:99]
	v_mfma_f32_16x16x32_bf16 v[92:95], v[154:157], v[228:231], v[92:95]
	v_mfma_f32_16x16x32_bf16 v[80:83], v[146:149], v[236:239], v[80:83]
	v_mfma_f32_16x16x32_bf16 v[76:79], v[154:157], v[236:239], v[76:79]
	s_setprio 1
	s_setprio 0
	v_mfma_f32_16x16x32_bf16 v[120:123], v[158:161], v[208:211], v[120:123]
	v_mfma_f32_16x16x32_bf16 v[116:119], v[180:183], v[208:211], v[116:119]
	v_mfma_f32_16x16x32_bf16 v[104:107], v[158:161], v[216:219], v[104:107]
	v_mfma_f32_16x16x32_bf16 v[100:103], v[180:183], v[216:219], v[100:103]
	v_mfma_f32_16x16x32_bf16 v[88:91], v[158:161], v[224:227], v[88:91]
	v_mfma_f32_16x16x32_bf16 v[84:87], v[180:183], v[224:227], v[84:87]
	v_mfma_f32_16x16x32_bf16 v[72:75], v[158:161], v[232:235], v[72:75]
	v_mfma_f32_16x16x32_bf16 v[68:71], v[180:183], v[232:235], v[68:71]
	v_mfma_f32_16x16x32_bf16 v[120:123], v[174:177], v[212:215], v[120:123]
	v_mfma_f32_16x16x32_bf16 v[116:119], v[204:207], v[212:215], v[116:119]
	v_mfma_f32_16x16x32_bf16 v[104:107], v[174:177], v[220:223], v[104:107]
	v_mfma_f32_16x16x32_bf16 v[100:103], v[204:207], v[220:223], v[100:103]
	v_mfma_f32_16x16x32_bf16 v[88:91], v[174:177], v[228:231], v[88:91]
	v_mfma_f32_16x16x32_bf16 v[84:87], v[204:207], v[228:231], v[84:87]
	v_mfma_f32_16x16x32_bf16 v[72:75], v[174:177], v[236:239], v[72:75]
	v_mfma_f32_16x16x32_bf16 v[68:71], v[204:207], v[236:239], v[68:71]
	s_setprio 1
	s_barrier
; #define PG8_STAGE(bufoff, gbase, voff) do { _Pragma("unroll") for (int _i = 0; _i < 2; ++_i) \
;         __builtin_amdgcn_global_load_lds((const unsigned*)((const char*)(gbase) + (voff)[_i]), (PG8_LAS unsigned*)(lds + (bufoff) + ldsw + _i * 8192), 16, 0, 0); } while (0)
; #define PG8_LDA(dst, b, h) do { _Pragma("unroll") for (int m = 0; m < 4; ++m) _Pragma("unroll") for (int k = 0; k < 2; ++k) dst[m][k] = *(const PG8_LAS bf16x8*)(lds + PG8_SA(b, h) + aoff + m * 2048 + k * 1024); } while (0)
; #define PG8_MMA(ai, bj, At, Bt) do { __builtin_amdgcn_s_setprio(1); _Pragma("unroll") for (int m = 0; m < 4; ++m) _Pragma("unroll") for (int n = 0; n < 2; ++n) _Pragma("unroll") for (int k = 0; k < 2; ++k) \
;         acc[ai][bj][m][n] = __builtin_amdgcn_mfma_f32_16x16x32_bf16(Bt[n][k], At[m][k], acc[ai][bj][m][n], 0, 0, 0); __builtin_amdgcn_s_setprio(0); } while (0)
; #define PG8_WAIT_V(n) asm volatile("s_waitcnt vmcnt(" #n ")" ::: "memory")
; #define PG8_WAIT_L(n) asm volatile("s_waitcnt lgkmcnt(" #n ")" ::: "memory")
; #define PG8_BAR __builtin_amdgcn_s_barrier()
; #define PG8_SCHED __builtin_amdgcn_sched_barrier(0)
; template <class Epi, class Sched, bool ALIGN_EPI = false, bool SP2 = false>
; __device__ __forceinline__ void gemm_phase(PG8_LAS unsigned char* lds, const Gemm g, const Sched& S, const Epi& E) {
;     ...
;             PG8_LDA(At, 1, 1); PG8_STAGE(PG8_SB(1, 0), b3, voffB); PG8_STAGE(PG8_SB(1, 1), b3 + hstep, voffB); PG8_STAGE(PG8_SA(1, 0), a3, voffA);
;             PG8_WAIT_V(8); PG8_WAIT_L(0); PG8_BAR; PG8_MMA(1, 0, At, B0); PG8_MMA(1, 1, At, B1); PG8_BAR; PG8_SCHED;
	s_add_i32 s34, s64, s46
	s_add_i32 m0, s34, 0xffffff80
	ds_read_b128 v[208:211], v179 offset:49152
	ds_read_b128 v[212:215], v179 offset:50176
	ds_read_b128 v[216:219], v179 offset:51200
	ds_read_b128 v[220:223], v179 offset:52224
	ds_read_b128 v[224:227], v179 offset:53248
	ds_read_b128 v[228:231], v179 offset:54272
	ds_read_b128 v[232:235], v179 offset:55296
	ds_read_b128 v[236:239], v179 offset:56320
	global_load_lds_dwordx4 v2, s[38:39] offset:128
	s_add_i32 m0, s34, 0x1f80
	s_add_u32 s34, s38, 0x158080
	s_addc_u32 s35, s39, 0
	global_load_lds_dwordx4 v132, s[38:39] offset:128
	s_add_i32 s38, s65, s46
	s_mov_b32 m0, s38
	s_nop 0
	global_load_lds_dwordx4 v2, s[34:35]
	s_add_i32 m0, s38, 0x2000
	s_nop 0
	global_load_lds_dwordx4 v132, s[34:35]
	s_add_i32 m0, s53, 0xffffff80
	s_nop 0
	global_load_lds_dwordx4 v2, s[40:41] offset:128
	s_add_i32 m0, s54, 0xffffff80
	s_nop 0
	global_load_lds_dwordx4 v132, s[40:41] offset:128
	s_nop 0
	s_waitcnt vmcnt(8)
	s_waitcnt lgkmcnt(0)
	s_barrier
	s_setprio 0
	s_waitcnt lgkmcnt(0)
	v_mfma_f32_16x16x32_bf16 v[64:67], v[142:145], v[208:211], v[64:67]
	v_mfma_f32_16x16x32_bf16 v[60:63], v[150:153], v[208:211], v[60:63]
	v_mfma_f32_16x16x32_bf16 v[48:51], v[142:145], v[216:219], v[48:51]
	v_mfma_f32_16x16x32_bf16 v[44:47], v[150:153], v[216:219], v[44:47]
	v_mfma_f32_16x16x32_bf16 v[32:35], v[142:145], v[224:227], v[32:35]
	v_mfma_f32_16x16x32_bf16 v[28:31], v[150:153], v[224:227], v[28:31]
	v_mfma_f32_16x16x32_bf16 v[16:19], v[142:145], v[232:235], v[16:19]
	v_mfma_f32_16x16x32_bf16 v[12:15], v[150:153], v[232:235], v[12:15]
	v_mfma_f32_16x16x32_bf16 v[64:67], v[146:149], v[212:215], v[64:67]
	v_mfma_f32_16x16x32_bf16 v[60:63], v[154:157], v[212:215], v[60:63]
	v_mfma_f32_16x16x32_bf16 v[48:51], v[146:149], v[220:223], v[48:51]
	v_mfma_f32_16x16x32_bf16 v[44:47], v[154:157], v[220:223], v[44:47]
	v_mfma_f32_16x16x32_bf16 v[32:35], v[146:149], v[228:231], v[32:35]
	v_mfma_f32_16x16x32_bf16 v[28:31], v[154:157], v[228:231], v[28:31]
	v_mfma_f32_16x16x32_bf16 v[16:19], v[146:149], v[236:239], v[16:19]
	v_mfma_f32_16x16x32_bf16 v[12:15], v[154:157], v[236:239], v[12:15]
	s_setprio 1
	s_setprio 0
	v_mfma_f32_16x16x32_bf16 v[56:59], v[158:161], v[208:211], v[56:59]
	v_mfma_f32_16x16x32_bf16 v[52:55], v[180:183], v[208:211], v[52:55]
	v_mfma_f32_16x16x32_bf16 v[40:43], v[158:161], v[216:219], v[40:43]
	v_mfma_f32_16x16x32_bf16 v[36:39], v[180:183], v[216:219], v[36:39]
	v_mfma_f32_16x16x32_bf16 v[24:27], v[158:161], v[224:227], v[24:27]
	v_mfma_f32_16x16x32_bf16 v[20:23], v[180:183], v[224:227], v[20:23]
	v_mfma_f32_16x16x32_bf16 v[8:11], v[158:161], v[232:235], v[8:11]
	v_mfma_f32_16x16x32_bf16 v[4:7], v[180:183], v[232:235], v[4:7]
	v_mfma_f32_16x16x32_bf16 v[56:59], v[174:177], v[212:215], v[56:59]
	v_mfma_f32_16x16x32_bf16 v[52:55], v[204:207], v[212:215], v[52:55]
	v_mfma_f32_16x16x32_bf16 v[40:43], v[174:177], v[220:223], v[40:43]
	v_mfma_f32_16x16x32_bf16 v[36:39], v[204:207], v[220:223], v[36:39]
	v_mfma_f32_16x16x32_bf16 v[24:27], v[174:177], v[228:231], v[24:27]
	v_mfma_f32_16x16x32_bf16 v[20:23], v[204:207], v[228:231], v[20:23]
	v_mfma_f32_16x16x32_bf16 v[8:11], v[174:177], v[236:239], v[8:11]
	v_mfma_f32_16x16x32_bf16 v[4:7], v[204:207], v[236:239], v[4:7]
	s_setprio 1
	s_barrier
	s_add_i32 s63, s63, 2
	s_add_u32 s61, s61, 0x100
	s_addc_u32 s62, s62, 0
	s_cmpk_gt_u32 s63, 0x53
	s_mov_b64 s[34:35], s[36:37]
	s_cbranch_scc0 .LBB0_575
	s_and_b64 vcc, exec, s[28:29]
	s_cbranch_vccz .LBB0_578
	s_barrier

; #define PG8_STAGE(bufoff, gbase, voff) do { _Pragma("unroll") for (int _i = 0; _i < 2; ++_i) \
;         __builtin_amdgcn_global_load_lds((const unsigned*)((const char*)(gbase) + (voff)[_i]), (PG8_LAS unsigned*)(lds + (bufoff) + ldsw + _i * 8192), 16, 0, 0); } while (0)
; #define PG8_LDA(dst, b, h) do { _Pragma("unroll") for (int m = 0; m < 4; ++m) _Pragma("unroll") for (int k = 0; k < 2; ++k) dst[m][k] = *(const PG8_LAS bf16x8*)(lds + PG8_SA(b, h) + aoff + m * 2048 + k * 1024); } while (0)
; #define PG8_LDB(dst, b, h) do { _Pragma("unroll") for (int n = 0; n < 2; ++n) _Pragma("unroll") for (int k = 0; k < 2; ++k) dst[n][k] = *(const PG8_LAS bf16x8*)(lds + PG8_SB(b, h) + boff + n * 2048 + k * 1024); } while (0)
; #define PG8_MMA(ai, bj, At, Bt) do { __builtin_amdgcn_s_setprio(1); _Pragma("unroll") for (int m = 0; m < 4; ++m) _Pragma("unroll") for (int n = 0; n < 2; ++n) _Pragma("unroll") for (int k = 0; k < 2; ++k) \
;         acc[ai][bj][m][n] = __builtin_amdgcn_mfma_f32_16x16x32_bf16(Bt[n][k], At[m][k], acc[ai][bj][m][n], 0, 0, 0); __builtin_amdgcn_s_setprio(0); } while (0)
; #define PG8_WAIT_V(n) asm volatile("s_waitcnt vmcnt(" #n ")" ::: "memory")
; #define PG8_WAIT_L(n) asm volatile("s_waitcnt lgkmcnt(" #n ")" ::: "memory")
; template <class Epi, class Sched, bool ALIGN_EPI = false, bool SP2 = false>
; __device__ __forceinline__ void gemm_phase(PG8_LAS unsigned char* lds, const Gemm g, const Sched& S, const Epi& E) {
;     ...
;             const bool last = (t == nt - 2);
;             const char* a1 = cA + (size_t)(t + 1) * kstep;
;             const char* a2 = last ? nA : cA + (size_t)(t + 2) * kstep; const char* b2 = last ? nB : cB + (size_t)(t + 2) * kstep;
;             const char* a3 = a2 + kstep; const char* b3 = b2 + kstep;
;             if (last && has_next) S.a_ready(nxt);
;             if constexpr (SP2) {
;             PG8_LDB(B0, 0, 0); PG8_LDB(B1, 0, 1); PG8_SCHED; PG8_LDA(At, 0, 0); PG8_STAGE(PG8_SA(1, 1), a1 + hstep, voffA);
;             PG8_WAIT_V(8); PG8_WAIT_L(0); PG8_BAR; PG8_MMA(0, 0, At, B0); PG8_MMA(0, 1, At, B1); PG8_BAR; PG8_SCHED;
;             PG8_LDA(At, 0, 1); PG8_STAGE(PG8_SB(0, 0), b2, voffB); PG8_STAGE(PG8_SB(0, 1), b2 + hstep, voffB); PG8_STAGE(PG8_SA(0, 0), a2, voffA);
;             PG8_WAIT_V(8); PG8_WAIT_L(0); PG8_BAR; PG8_MMA(1, 0, At, B0); PG8_MMA(1, 1, At, B1); PG8_BAR; PG8_SCHED;
.LBB0_674:
	s_add_u32 s42, s40, 0xfff80080
	s_addc_u32 s43, s41, -1
	s_add_i32 s64, 0, 0x10000
	s_cmp_eq_u32 s63, 28
	s_cselect_b32 s45, s5, s43
	s_cselect_b32 s44, s4, s42
	s_cselect_b32 s43, s37, s62
	s_cselect_b32 s42, s36, s35
	s_add_i32 s66, 0, 0x14000
	v_add_u32_e32 v144, s64, v173
	v_add_u32_e32 v162, s66, v173
	ds_read_b128 v[132:135], v144
	ds_read_b128 v[136:139], v144 offset:1024
	ds_read_b128 v[140:143], v144 offset:2048
	ds_read_b128 v[144:147], v144 offset:3072
	ds_read_b128 v[158:161], v162
	ds_read_b128 v[174:177], v162 offset:1024
	ds_read_b128 v[206:209], v162 offset:2048
	ds_read_b128 v[210:213], v162 offset:3072
	s_add_i32 m0, s39, 0xc000
	ds_read_b128 v[214:217], v204
	ds_read_b128 v[218:221], v204 offset:1024
	ds_read_b128 v[222:225], v204 offset:2048
	ds_read_b128 v[226:229], v204 offset:3072
	ds_read_b128 v[230:233], v204 offset:4096
	ds_read_b128 v[234:237], v204 offset:5120
	ds_read_b128 v[238:241], v204 offset:6144
	ds_read_b128 v[242:245], v204 offset:7168
	global_load_lds_dwordx4 v154, s[40:41]
	s_add_i32 m0, s39, 0xe000
	s_nop 0
	global_load_lds_dwordx4 v156, s[40:41]
	s_waitcnt vmcnt(8)
	s_waitcnt lgkmcnt(0)
	s_barrier
	s_setprio 0
	s_waitcnt lgkmcnt(0)
	v_mfma_f32_16x16x32_bf16 v[128:131], v[132:135], v[214:217], v[128:131]
	v_mfma_f32_16x16x32_bf16 v[124:127], v[140:143], v[214:217], v[124:127]
	v_mfma_f32_16x16x32_bf16 v[116:119], v[132:135], v[222:225], v[116:119]
	v_mfma_f32_16x16x32_bf16 v[108:111], v[140:143], v[222:225], v[108:111]
	v_mfma_f32_16x16x32_bf16 v[100:103], v[132:135], v[230:233], v[100:103]
	v_mfma_f32_16x16x32_bf16 v[92:95], v[140:143], v[230:233], v[92:95]
	v_mfma_f32_16x16x32_bf16 v[84:87], v[132:135], v[238:241], v[84:87]
	v_mfma_f32_16x16x32_bf16 v[76:79], v[140:143], v[238:241], v[76:79]
	v_mfma_f32_16x16x32_bf16 v[128:131], v[136:139], v[218:221], v[128:131]
	v_mfma_f32_16x16x32_bf16 v[124:127], v[144:147], v[218:221], v[124:127]
	v_mfma_f32_16x16x32_bf16 v[116:119], v[136:139], v[226:229], v[116:119]
	v_mfma_f32_16x16x32_bf16 v[108:111], v[144:147], v[226:229], v[108:111]
	v_mfma_f32_16x16x32_bf16 v[100:103], v[136:139], v[234:237], v[100:103]
	v_mfma_f32_16x16x32_bf16 v[92:95], v[144:147], v[234:237], v[92:95]
	v_mfma_f32_16x16x32_bf16 v[84:87], v[136:139], v[242:245], v[84:87]
	v_mfma_f32_16x16x32_bf16 v[76:79], v[144:147], v[242:245], v[76:79]
	s_setprio 1
	s_setprio 0
	v_mfma_f32_16x16x32_bf16 v[120:123], v[158:161], v[214:217], v[120:123]
	v_mfma_f32_16x16x32_bf16 v[112:115], v[206:209], v[214:217], v[112:115]
	v_mfma_f32_16x16x32_bf16 v[104:107], v[158:161], v[222:225], v[104:107]
	v_mfma_f32_16x16x32_bf16 v[96:99], v[206:209], v[222:225], v[96:99]
	v_mfma_f32_16x16x32_bf16 v[88:91], v[158:161], v[230:233], v[88:91]
	v_mfma_f32_16x16x32_bf16 v[80:83], v[206:209], v[230:233], v[80:83]
	v_mfma_f32_16x16x32_bf16 v[72:75], v[158:161], v[238:241], v[72:75]
	v_mfma_f32_16x16x32_bf16 v[68:71], v[206:209], v[238:241], v[68:71]
	v_mfma_f32_16x16x32_bf16 v[120:123], v[174:177], v[218:221], v[120:123]
	v_mfma_f32_16x16x32_bf16 v[112:115], v[210:213], v[218:221], v[112:115]
	v_mfma_f32_16x16x32_bf16 v[104:107], v[174:177], v[226:229], v[104:107]
	v_mfma_f32_16x16x32_bf16 v[96:99], v[210:213], v[226:229], v[96:99]
	v_mfma_f32_16x16x32_bf16 v[88:91], v[174:177], v[234:237], v[88:91]
	v_mfma_f32_16x16x32_bf16 v[80:83], v[210:213], v[234:237], v[80:83]
	v_mfma_f32_16x16x32_bf16 v[72:75], v[174:177], v[242:245], v[72:75]
	v_mfma_f32_16x16x32_bf16 v[68:71], v[210:213], v[242:245], v[68:71]
	s_setprio 1
	s_barrier
	s_add_i32 s64, s64, s46
	s_mov_b32 m0, s64
	ds_read_b128 v[214:217], v204 offset:16384
	ds_read_b128 v[218:221], v204 offset:17408
	ds_read_b128 v[222:225], v204 offset:18432
	ds_read_b128 v[226:229], v204 offset:19456
	ds_read_b128 v[230:233], v204 offset:20480
	ds_read_b128 v[234:237], v204 offset:21504
	ds_read_b128 v[238:241], v204 offset:22528
	ds_read_b128 v[242:245], v204 offset:23552
	global_load_lds_dwordx4 v2, s[42:43]
	s_add_i32 m0, s64, 0x2000
	s_add_u32 s64, s42, 0x80000
	s_addc_u32 s65, s43, 0
	s_add_i32 s66, s66, s46
	global_load_lds_dwordx4 v148, s[42:43]
	s_mov_b32 m0, s66
	s_nop 0
	global_load_lds_dwordx4 v2, s[64:65]
	s_add_i32 m0, s66, 0x2000
	s_nop 0
	global_load_lds_dwordx4 v148, s[64:65]
	s_mov_b32 m0, s39
	s_nop 0
	global_load_lds_dwordx4 v152, s[44:45]
	s_mov_b32 m0, s51
	s_nop 0
	global_load_lds_dwordx4 v150, s[44:45]
	s_waitcnt vmcnt(8)
	s_waitcnt lgkmcnt(0)
	s_barrier
	s_setprio 0
	s_waitcnt lgkmcnt(0)
	v_mfma_f32_16x16x32_bf16 v[64:67], v[132:135], v[214:217], v[64:67]
	v_mfma_f32_16x16x32_bf16 v[60:63], v[140:143], v[214:217], v[60:63]
	v_mfma_f32_16x16x32_bf16 v[52:55], v[132:135], v[222:225], v[52:55]
	v_mfma_f32_16x16x32_bf16 v[44:47], v[140:143], v[222:225], v[44:47]
	v_mfma_f32_16x16x32_bf16 v[36:39], v[132:135], v[230:233], v[36:39]
	v_mfma_f32_16x16x32_bf16 v[28:31], v[140:143], v[230:233], v[28:31]
	v_mfma_f32_16x16x32_bf16 v[20:23], v[132:135], v[238:241], v[20:23]
	v_mfma_f32_16x16x32_bf16 v[12:15], v[140:143], v[238:241], v[12:15]
	v_mfma_f32_16x16x32_bf16 v[64:67], v[136:139], v[218:221], v[64:67]
	v_mfma_f32_16x16x32_bf16 v[60:63], v[144:147], v[218:221], v[60:63]
	v_mfma_f32_16x16x32_bf16 v[52:55], v[136:139], v[226:229], v[52:55]
	v_mfma_f32_16x16x32_bf16 v[44:47], v[144:147], v[226:229], v[44:47]
	v_mfma_f32_16x16x32_bf16 v[36:39], v[136:139], v[234:237], v[36:39]
	v_mfma_f32_16x16x32_bf16 v[28:31], v[144:147], v[234:237], v[28:31]
	v_mfma_f32_16x16x32_bf16 v[20:23], v[136:139], v[242:245], v[20:23]
	v_mfma_f32_16x16x32_bf16 v[12:15], v[144:147], v[242:245], v[12:15]
	s_setprio 1
	s_setprio 0
	v_mfma_f32_16x16x32_bf16 v[56:59], v[158:161], v[214:217], v[56:59]
	v_mfma_f32_16x16x32_bf16 v[48:51], v[206:209], v[214:217], v[48:51]
	v_mfma_f32_16x16x32_bf16 v[40:43], v[158:161], v[222:225], v[40:43]
	v_mfma_f32_16x16x32_bf16 v[32:35], v[206:209], v[222:225], v[32:35]
	v_mfma_f32_16x16x32_bf16 v[24:27], v[158:161], v[230:233], v[24:27]
	v_mfma_f32_16x16x32_bf16 v[16:19], v[206:209], v[230:233], v[16:19]
	v_mfma_f32_16x16x32_bf16 v[8:11], v[158:161], v[238:241], v[8:11]
	v_mfma_f32_16x16x32_bf16 v[4:7], v[206:209], v[238:241], v[4:7]
	v_mfma_f32_16x16x32_bf16 v[56:59], v[174:177], v[218:221], v[56:59]
	v_mfma_f32_16x16x32_bf16 v[48:51], v[210:213], v[218:221], v[48:51]
	v_mfma_f32_16x16x32_bf16 v[40:43], v[174:177], v[226:229], v[40:43]
	v_mfma_f32_16x16x32_bf16 v[32:35], v[210:213], v[226:229], v[32:35]
	v_mfma_f32_16x16x32_bf16 v[24:27], v[174:177], v[234:237], v[24:27]
	v_mfma_f32_16x16x32_bf16 v[16:19], v[210:213], v[234:237], v[16:19]
	v_mfma_f32_16x16x32_bf16 v[8:11], v[174:177], v[242:245], v[8:11]
	v_mfma_f32_16x16x32_bf16 v[4:7], v[210:213], v[242:245], v[4:7]
	s_setprio 1
	s_barrier
; #define PG8_STAGE(bufoff, gbase, voff) do { _Pragma("unroll") for (int _i = 0; _i < 2; ++_i) \
;         __builtin_amdgcn_global_load_lds((const unsigned*)((const char*)(gbase) + (voff)[_i]), (PG8_LAS unsigned*)(lds + (bufoff) + ldsw + _i * 8192), 16, 0, 0); } while (0)
; #define PG8_LDA(dst, b, h) do { _Pragma("unroll") for (int m = 0; m < 4; ++m) _Pragma("unroll") for (int k = 0; k < 2; ++k) dst[m][k] = *(const PG8_LAS bf16x8*)(lds + PG8_SA(b, h) + aoff + m * 2048 + k * 1024); } while (0)
; #define PG8_LDB(dst, b, h) do { _Pragma("unroll") for (int n = 0; n < 2; ++n) _Pragma("unroll") for (int k = 0; k < 2; ++k) dst[n][k] = *(const PG8_LAS bf16x8*)(lds + PG8_SB(b, h) + boff + n * 2048 + k * 1024); } while (0)
; #define PG8_MMA(ai, bj, At, Bt) do { __builtin_amdgcn_s_setprio(1); _Pragma("unroll") for (int m = 0; m < 4; ++m) _Pragma("unroll") for (int n = 0; n < 2; ++n) _Pragma("unroll") for (int k = 0; k < 2; ++k) \
;         acc[ai][bj][m][n] = __builtin_amdgcn_mfma_f32_16x16x32_bf16(Bt[n][k], At[m][k], acc[ai][bj][m][n], 0, 0, 0); __builtin_amdgcn_s_setprio(0); } while (0)
; #define PG8_WAIT_V(n) asm volatile("s_waitcnt vmcnt(" #n ")" ::: "memory")
; #define PG8_WAIT_L(n) asm volatile("s_waitcnt lgkmcnt(" #n ")" ::: "memory")
; #define PG8_BAR __builtin_amdgcn_s_barrier()
; #define PG8_SCHED __builtin_amdgcn_sched_barrier(0)
; template <class Epi, class Sched, bool ALIGN_EPI = false, bool SP2 = false>
; __device__ __forceinline__ void gemm_phase(PG8_LAS unsigned char* lds, const Gemm g, const Sched& S, const Epi& E) {
;     ...
;             PG8_LDB(B0, 1, 0); PG8_LDB(B1, 1, 1); PG8_SCHED; PG8_LDA(At, 1, 0); PG8_STAGE(PG8_SA(0, 1), a2 + hstep, voffA);
;             PG8_WAIT_V(8); PG8_WAIT_L(0); PG8_BAR; PG8_MMA(0, 0, At, B0); PG8_MMA(0, 1, At, B1); PG8_BAR; PG8_SCHED;
;             PG8_LDA(At, 1, 1); PG8_STAGE(PG8_SB(1, 0), b3, voffB); PG8_STAGE(PG8_SB(1, 1), b3 + hstep, voffB); PG8_STAGE(PG8_SA(1, 0), a3, voffA);
;             PG8_WAIT_V(8); PG8_WAIT_L(0); PG8_BAR; PG8_MMA(1, 0, At, B0); PG8_MMA(1, 1, At, B1); PG8_BAR; PG8_SCHED;
	s_add_i32 s64, 0, 0x18000
	s_add_i32 s65, 0, 0x1c000
	v_add_u32_e32 v144, s64, v173
	v_add_u32_e32 v164, s65, v173
	ds_read_b128 v[132:135], v144
	ds_read_b128 v[136:139], v144 offset:1024
	ds_read_b128 v[140:143], v144 offset:2048
	ds_read_b128 v[144:147], v144 offset:3072
	ds_read_b128 v[158:161], v164
	ds_read_b128 v[174:177], v164 offset:1024
	ds_read_b128 v[206:209], v164 offset:2048
	ds_read_b128 v[210:213], v164 offset:3072
	s_add_u32 s100, s44, 0x80
	s_addc_u32 s101, s45, 0
	s_add_u32 s44, s44, 0x80000
	s_addc_u32 s45, s45, 0
	s_mov_b32 m0, s52
	ds_read_b128 v[214:217], v204 offset:32768
	ds_read_b128 v[218:221], v204 offset:33792
	ds_read_b128 v[222:225], v204 offset:34816
	ds_read_b128 v[226:229], v204 offset:35840
	ds_read_b128 v[230:233], v204 offset:36864
	ds_read_b128 v[234:237], v204 offset:37888
	ds_read_b128 v[238:241], v204 offset:38912
	ds_read_b128 v[242:245], v204 offset:39936
	global_load_lds_dwordx4 v152, s[44:45]
	s_mov_b32 m0, s53
	s_nop 0
	global_load_lds_dwordx4 v150, s[44:45]
	s_waitcnt vmcnt(8)
	s_waitcnt lgkmcnt(0)
	s_barrier
	s_setprio 0
	s_waitcnt lgkmcnt(0)
	v_mfma_f32_16x16x32_bf16 v[128:131], v[132:135], v[214:217], v[128:131]
	v_mfma_f32_16x16x32_bf16 v[124:127], v[140:143], v[214:217], v[124:127]
	v_mfma_f32_16x16x32_bf16 v[116:119], v[132:135], v[222:225], v[116:119]
	v_mfma_f32_16x16x32_bf16 v[108:111], v[140:143], v[222:225], v[108:111]
	v_mfma_f32_16x16x32_bf16 v[100:103], v[132:135], v[230:233], v[100:103]
	v_mfma_f32_16x16x32_bf16 v[92:95], v[140:143], v[230:233], v[92:95]
	v_mfma_f32_16x16x32_bf16 v[84:87], v[132:135], v[238:241], v[84:87]
	v_mfma_f32_16x16x32_bf16 v[76:79], v[140:143], v[238:241], v[76:79]
	v_mfma_f32_16x16x32_bf16 v[128:131], v[136:139], v[218:221], v[128:131]
	v_mfma_f32_16x16x32_bf16 v[124:127], v[144:147], v[218:221], v[124:127]
	v_mfma_f32_16x16x32_bf16 v[116:119], v[136:139], v[226:229], v[116:119]
	v_mfma_f32_16x16x32_bf16 v[108:111], v[144:147], v[226:229], v[108:111]
	v_mfma_f32_16x16x32_bf16 v[100:103], v[136:139], v[234:237], v[100:103]
	v_mfma_f32_16x16x32_bf16 v[92:95], v[144:147], v[234:237], v[92:95]
	v_mfma_f32_16x16x32_bf16 v[84:87], v[136:139], v[242:245], v[84:87]
	v_mfma_f32_16x16x32_bf16 v[76:79], v[144:147], v[242:245], v[76:79]
	s_setprio 1
	s_setprio 0
	v_mfma_f32_16x16x32_bf16 v[120:123], v[158:161], v[214:217], v[120:123]
	v_mfma_f32_16x16x32_bf16 v[112:115], v[206:209], v[214:217], v[112:115]
	v_mfma_f32_16x16x32_bf16 v[104:107], v[158:161], v[222:225], v[104:107]
	v_mfma_f32_16x16x32_bf16 v[96:99], v[206:209], v[222:225], v[96:99]
	v_mfma_f32_16x16x32_bf16 v[88:91], v[158:161], v[230:233], v[88:91]
	v_mfma_f32_16x16x32_bf16 v[80:83], v[206:209], v[230:233], v[80:83]
	v_mfma_f32_16x16x32_bf16 v[72:75], v[158:161], v[238:241], v[72:75]
	v_mfma_f32_16x16x32_bf16 v[68:71], v[206:209], v[238:241], v[68:71]
	v_mfma_f32_16x16x32_bf16 v[120:123], v[174:177], v[218:221], v[120:123]
	v_mfma_f32_16x16x32_bf16 v[112:115], v[210:213], v[218:221], v[112:115]
	v_mfma_f32_16x16x32_bf16 v[104:107], v[174:177], v[226:229], v[104:107]
	v_mfma_f32_16x16x32_bf16 v[96:99], v[210:213], v[226:229], v[96:99]
	v_mfma_f32_16x16x32_bf16 v[88:91], v[174:177], v[234:237], v[88:91]
	v_mfma_f32_16x16x32_bf16 v[80:83], v[210:213], v[234:237], v[80:83]
	v_mfma_f32_16x16x32_bf16 v[72:75], v[174:177], v[242:245], v[72:75]
	v_mfma_f32_16x16x32_bf16 v[68:71], v[210:213], v[242:245], v[68:71]
	s_setprio 1
	s_barrier
	s_add_i32 s44, s64, s46
	s_add_i32 m0, s44, 0xffffff80
	ds_read_b128 v[214:217], v204 offset:49152
	ds_read_b128 v[218:221], v204 offset:50176
	ds_read_b128 v[222:225], v204 offset:51200
	ds_read_b128 v[226:229], v204 offset:52224
	ds_read_b128 v[230:233], v204 offset:53248
	ds_read_b128 v[234:237], v204 offset:54272
	ds_read_b128 v[238:241], v204 offset:55296
	ds_read_b128 v[242:245], v204 offset:56320
	global_load_lds_dwordx4 v2, s[42:43] offset:128
	s_add_i32 m0, s44, 0x1f80
	s_add_i32 s44, s65, s46
	global_load_lds_dwordx4 v148, s[42:43] offset:128
	s_add_u32 s42, s42, 0x80080
	s_addc_u32 s43, s43, 0
	s_mov_b32 m0, s44
	s_nop 0
	global_load_lds_dwordx4 v2, s[42:43]
	s_add_i32 m0, s44, 0x2000
	s_nop 0
	global_load_lds_dwordx4 v148, s[42:43]
	s_mov_b32 m0, s54
	s_nop 0
	global_load_lds_dwordx4 v152, s[100:101]
	s_mov_b32 m0, s55
	s_nop 0
	global_load_lds_dwordx4 v150, s[100:101]
	s_nop 0
	s_waitcnt vmcnt(8)
	s_waitcnt lgkmcnt(0)
	s_barrier
	s_setprio 0
	s_waitcnt lgkmcnt(0)
	v_mfma_f32_16x16x32_bf16 v[64:67], v[132:135], v[214:217], v[64:67]
	v_mfma_f32_16x16x32_bf16 v[60:63], v[140:143], v[214:217], v[60:63]
	v_mfma_f32_16x16x32_bf16 v[52:55], v[132:135], v[222:225], v[52:55]
	v_mfma_f32_16x16x32_bf16 v[44:47], v[140:143], v[222:225], v[44:47]
	v_mfma_f32_16x16x32_bf16 v[36:39], v[132:135], v[230:233], v[36:39]
	v_mfma_f32_16x16x32_bf16 v[28:31], v[140:143], v[230:233], v[28:31]
	v_mfma_f32_16x16x32_bf16 v[20:23], v[132:135], v[238:241], v[20:23]
	v_mfma_f32_16x16x32_bf16 v[12:15], v[140:143], v[238:241], v[12:15]
	v_mfma_f32_16x16x32_bf16 v[64:67], v[136:139], v[218:221], v[64:67]
	v_mfma_f32_16x16x32_bf16 v[60:63], v[144:147], v[218:221], v[60:63]
	v_mfma_f32_16x16x32_bf16 v[52:55], v[136:139], v[226:229], v[52:55]
	v_mfma_f32_16x16x32_bf16 v[44:47], v[144:147], v[226:229], v[44:47]
	v_mfma_f32_16x16x32_bf16 v[36:39], v[136:139], v[234:237], v[36:39]
	v_mfma_f32_16x16x32_bf16 v[28:31], v[144:147], v[234:237], v[28:31]
	v_mfma_f32_16x16x32_bf16 v[20:23], v[136:139], v[242:245], v[20:23]
	v_mfma_f32_16x16x32_bf16 v[12:15], v[144:147], v[242:245], v[12:15]
	s_setprio 1
	s_setprio 0
	v_mfma_f32_16x16x32_bf16 v[56:59], v[158:161], v[214:217], v[56:59]
	v_mfma_f32_16x16x32_bf16 v[48:51], v[206:209], v[214:217], v[48:51]
	v_mfma_f32_16x16x32_bf16 v[40:43], v[158:161], v[222:225], v[40:43]
	v_mfma_f32_16x16x32_bf16 v[32:35], v[206:209], v[222:225], v[32:35]
	v_mfma_f32_16x16x32_bf16 v[24:27], v[158:161], v[230:233], v[24:27]
	v_mfma_f32_16x16x32_bf16 v[16:19], v[206:209], v[230:233], v[16:19]
	v_mfma_f32_16x16x32_bf16 v[8:11], v[158:161], v[238:241], v[8:11]
	v_mfma_f32_16x16x32_bf16 v[4:7], v[206:209], v[238:241], v[4:7]
	v_mfma_f32_16x16x32_bf16 v[56:59], v[174:177], v[218:221], v[56:59]
	v_mfma_f32_16x16x32_bf16 v[48:51], v[210:213], v[218:221], v[48:51]
	v_mfma_f32_16x16x32_bf16 v[40:43], v[174:177], v[226:229], v[40:43]
	v_mfma_f32_16x16x32_bf16 v[32:35], v[210:213], v[226:229], v[32:35]
	v_mfma_f32_16x16x32_bf16 v[24:27], v[174:177], v[234:237], v[24:27]
	v_mfma_f32_16x16x32_bf16 v[16:19], v[210:213], v[234:237], v[16:19]
	v_mfma_f32_16x16x32_bf16 v[8:11], v[174:177], v[242:245], v[8:11]
	v_mfma_f32_16x16x32_bf16 v[4:7], v[210:213], v[242:245], v[4:7]
	s_setprio 1
	s_barrier
	s_add_i32 s63, s63, 2
	s_add_u32 s40, s40, 0x100
	s_addc_u32 s41, s41, 0
	s_add_u32 s35, s35, 0x100
	s_addc_u32 s62, s62, 0
	s_cmp_gt_u32 s63, 29
	s_cbranch_scc0 .LBB0_674
	s_and_b64 vcc, exec, s[30:31]
	s_cbranch_vccz .LBB0_677
	s_barrier

; #define PG8_STAGE(bufoff, gbase, voff) do { _Pragma("unroll") for (int _i = 0; _i < 2; ++_i) \
;         __builtin_amdgcn_global_load_lds((const unsigned*)((const char*)(gbase) + (voff)[_i]), (PG8_LAS unsigned*)(lds + (bufoff) + ldsw + _i * 8192), 16, 0, 0); } while (0)
; #define PG8_LDA(dst, b, h) do { _Pragma("unroll") for (int m = 0; m < 4; ++m) _Pragma("unroll") for (int k = 0; k < 2; ++k) dst[m][k] = *(const PG8_LAS bf16x8*)(lds + PG8_SA(b, h) + aoff + m * 2048 + k * 1024); } while (0)
; #define PG8_LDB(dst, b, h) do { _Pragma("unroll") for (int n = 0; n < 2; ++n) _Pragma("unroll") for (int k = 0; k < 2; ++k) dst[n][k] = *(const PG8_LAS bf16x8*)(lds + PG8_SB(b, h) + boff + n * 2048 + k * 1024); } while (0)
; #define PG8_MMA(ai, bj, At, Bt) do { __builtin_amdgcn_s_setprio(1); _Pragma("unroll") for (int m = 0; m < 4; ++m) _Pragma("unroll") for (int n = 0; n < 2; ++n) _Pragma("unroll") for (int k = 0; k < 2; ++k) \
;         acc[ai][bj][m][n] = __builtin_amdgcn_mfma_f32_16x16x32_bf16(Bt[n][k], At[m][k], acc[ai][bj][m][n], 0, 0, 0); __builtin_amdgcn_s_setprio(0); } while (0)
; #define PG8_WAIT_V(n) asm volatile("s_waitcnt vmcnt(" #n ")" ::: "memory")
; #define PG8_WAIT_L(n) asm volatile("s_waitcnt lgkmcnt(" #n ")" ::: "memory")
; template <class Epi, class Sched, bool ALIGN_EPI = false, bool SP2 = false>
; __device__ __forceinline__ void gemm_phase(PG8_LAS unsigned char* lds, const Gemm g, const Sched& S, const Epi& E) {
;     ...
;             const bool last = (t == nt - 2);
;             const char* a1 = cA + (size_t)(t + 1) * kstep;
;             const char* a2 = last ? nA : cA + (size_t)(t + 2) * kstep; const char* b2 = last ? nB : cB + (size_t)(t + 2) * kstep;
;             const char* a3 = a2 + kstep; const char* b3 = b2 + kstep;
;             if (last && has_next) S.a_ready(nxt);
;             if constexpr (SP2) {
;             PG8_LDB(B0, 0, 0); PG8_LDB(B1, 0, 1); PG8_SCHED; PG8_LDA(At, 0, 0); PG8_STAGE(PG8_SA(1, 1), a1 + hstep, voffA);
;             PG8_WAIT_V(8); PG8_WAIT_L(0); PG8_BAR; PG8_MMA(0, 0, At, B0); PG8_MMA(0, 1, At, B1); PG8_BAR; PG8_SCHED;
;             PG8_LDA(At, 0, 1); PG8_STAGE(PG8_SB(0, 0), b2, voffB); PG8_STAGE(PG8_SB(0, 1), b2 + hstep, voffB); PG8_STAGE(PG8_SA(0, 0), a2, voffA);
;             PG8_WAIT_V(8); PG8_WAIT_L(0); PG8_BAR; PG8_MMA(1, 0, At, B0); PG8_MMA(1, 1, At, B1); PG8_BAR; PG8_SCHED;
.LBB0_2096:
	s_add_u32 s27, s40, 0xfffc0080
	s_addc_u32 s29, s41, -1
	s_add_i32 s31, 0, 0x10000
	s_cmp_eq_u32 s26, 12
	s_cselect_b32 s45, s1, s29
	s_cselect_b32 s44, s0, s27
	v_add_u32_e32 v2, s31, v173
	s_cselect_b32 s43, s35, s13
	s_cselect_b32 s42, s34, s11
	s_add_i32 s27, 0, 0x14000
	ds_read_b128 v[134:137], v2
	ds_read_b128 v[138:141], v2 offset:1024
	ds_read_b128 v[154:157], v2 offset:2048
	ds_read_b128 v[158:161], v2 offset:3072
	v_add_u32_e32 v2, s27, v173
	ds_read_b128 v[178:181], v2
	ds_read_b128 v[204:207], v2 offset:1024
	ds_read_b128 v[208:211], v2 offset:2048
	ds_read_b128 v[212:215], v2 offset:3072
	s_add_i32 m0, s55, 0xc000
	ds_read_b128 v[216:219], v177
	ds_read_b128 v[220:223], v177 offset:1024
	ds_read_b128 v[224:227], v177 offset:2048
	ds_read_b128 v[228:231], v177 offset:3072
	ds_read_b128 v[232:235], v177 offset:4096
	ds_read_b128 v[236:239], v177 offset:5120
	ds_read_b128 v[240:243], v177 offset:6144
	ds_read_b128 v[244:247], v177 offset:7168
	global_load_lds_dwordx4 v150, s[40:41]
	s_add_i32 m0, s55, 0xe000
	s_nop 0
	global_load_lds_dwordx4 v152, s[40:41]
	s_waitcnt vmcnt(8)
	s_waitcnt lgkmcnt(0)
	s_barrier
	s_setprio 0
	s_waitcnt lgkmcnt(0)
	v_mfma_f32_16x16x32_bf16 v[130:133], v[134:137], v[216:219], v[130:133]
	v_mfma_f32_16x16x32_bf16 v[126:129], v[154:157], v[216:219], v[126:129]
	v_mfma_f32_16x16x32_bf16 v[122:125], v[134:137], v[224:227], v[122:125]
	v_mfma_f32_16x16x32_bf16 v[118:121], v[154:157], v[224:227], v[118:121]
	v_mfma_f32_16x16x32_bf16 v[114:117], v[134:137], v[232:235], v[114:117]
	v_mfma_f32_16x16x32_bf16 v[110:113], v[154:157], v[232:235], v[110:113]
	v_mfma_f32_16x16x32_bf16 v[106:109], v[134:137], v[240:243], v[106:109]
	v_mfma_f32_16x16x32_bf16 v[102:105], v[154:157], v[240:243], v[102:105]
	v_mfma_f32_16x16x32_bf16 v[130:133], v[138:141], v[220:223], v[130:133]
	v_mfma_f32_16x16x32_bf16 v[126:129], v[158:161], v[220:223], v[126:129]
	v_mfma_f32_16x16x32_bf16 v[122:125], v[138:141], v[228:231], v[122:125]
	v_mfma_f32_16x16x32_bf16 v[118:121], v[158:161], v[228:231], v[118:121]
	v_mfma_f32_16x16x32_bf16 v[114:117], v[138:141], v[236:239], v[114:117]
	v_mfma_f32_16x16x32_bf16 v[110:113], v[158:161], v[236:239], v[110:113]
	v_mfma_f32_16x16x32_bf16 v[106:109], v[138:141], v[244:247], v[106:109]
	v_mfma_f32_16x16x32_bf16 v[102:105], v[158:161], v[244:247], v[102:105]
	s_setprio 1
	s_setprio 0
	v_mfma_f32_16x16x32_bf16 v[98:101], v[178:181], v[216:219], v[98:101]
	v_mfma_f32_16x16x32_bf16 v[94:97], v[208:211], v[216:219], v[94:97]
	v_mfma_f32_16x16x32_bf16 v[90:93], v[178:181], v[224:227], v[90:93]
	v_mfma_f32_16x16x32_bf16 v[86:89], v[208:211], v[224:227], v[86:89]
	v_mfma_f32_16x16x32_bf16 v[82:85], v[178:181], v[232:235], v[82:85]
	v_mfma_f32_16x16x32_bf16 v[78:81], v[208:211], v[232:235], v[78:81]
	v_mfma_f32_16x16x32_bf16 v[74:77], v[178:181], v[240:243], v[74:77]
	v_mfma_f32_16x16x32_bf16 v[70:73], v[208:211], v[240:243], v[70:73]
	v_mfma_f32_16x16x32_bf16 v[98:101], v[204:207], v[220:223], v[98:101]
	v_mfma_f32_16x16x32_bf16 v[94:97], v[212:215], v[220:223], v[94:97]
	v_mfma_f32_16x16x32_bf16 v[90:93], v[204:207], v[228:231], v[90:93]
	v_mfma_f32_16x16x32_bf16 v[86:89], v[212:215], v[228:231], v[86:89]
	v_mfma_f32_16x16x32_bf16 v[82:85], v[204:207], v[236:239], v[82:85]
	v_mfma_f32_16x16x32_bf16 v[78:81], v[212:215], v[236:239], v[78:81]
	v_mfma_f32_16x16x32_bf16 v[74:77], v[204:207], v[244:247], v[74:77]
	v_mfma_f32_16x16x32_bf16 v[70:73], v[212:215], v[244:247], v[70:73]
	s_setprio 1
	s_barrier
	s_add_i32 s29, s31, s54
	s_mov_b32 m0, s29
	ds_read_b128 v[216:219], v177 offset:16384
	ds_read_b128 v[220:223], v177 offset:17408
	ds_read_b128 v[224:227], v177 offset:18432
	ds_read_b128 v[228:231], v177 offset:19456
	ds_read_b128 v[232:235], v177 offset:20480
	ds_read_b128 v[236:239], v177 offset:21504
	ds_read_b128 v[240:243], v177 offset:22528
	ds_read_b128 v[244:247], v177 offset:23552
	global_load_lds_dwordx4 v144, s[42:43]
	s_add_i32 m0, s29, 0x2000
	s_add_u32 s64, s42, 0x40000
	s_addc_u32 s65, s43, 0
	s_add_i32 s27, s27, s54
	global_load_lds_dwordx4 v148, s[42:43]
	s_mov_b32 m0, s27
	s_nop 0
	global_load_lds_dwordx4 v144, s[64:65]
	s_add_i32 m0, s27, 0x2000
	s_nop 0
	global_load_lds_dwordx4 v148, s[64:65]
	s_mov_b32 m0, s55
	s_nop 0
	global_load_lds_dwordx4 v142, s[44:45]
	s_mov_b32 m0, s56
	s_nop 0
	global_load_lds_dwordx4 v146, s[44:45]
	s_waitcnt vmcnt(8)
	s_waitcnt lgkmcnt(0)
	s_barrier
	s_setprio 0
	s_waitcnt lgkmcnt(0)
	v_mfma_f32_16x16x32_bf16 v[66:69], v[134:137], v[216:219], v[66:69]
	v_mfma_f32_16x16x32_bf16 v[62:65], v[154:157], v[216:219], v[62:65]
	v_mfma_f32_16x16x32_bf16 v[58:61], v[134:137], v[224:227], v[58:61]
	v_mfma_f32_16x16x32_bf16 v[54:57], v[154:157], v[224:227], v[54:57]
	v_mfma_f32_16x16x32_bf16 v[50:53], v[134:137], v[232:235], v[50:53]
	v_mfma_f32_16x16x32_bf16 v[46:49], v[154:157], v[232:235], v[46:49]
	v_mfma_f32_16x16x32_bf16 v[42:45], v[134:137], v[240:243], v[42:45]
	v_mfma_f32_16x16x32_bf16 v[38:41], v[154:157], v[240:243], v[38:41]
	v_mfma_f32_16x16x32_bf16 v[66:69], v[138:141], v[220:223], v[66:69]
	v_mfma_f32_16x16x32_bf16 v[62:65], v[158:161], v[220:223], v[62:65]
	v_mfma_f32_16x16x32_bf16 v[58:61], v[138:141], v[228:231], v[58:61]
	v_mfma_f32_16x16x32_bf16 v[54:57], v[158:161], v[228:231], v[54:57]
	v_mfma_f32_16x16x32_bf16 v[50:53], v[138:141], v[236:239], v[50:53]
	v_mfma_f32_16x16x32_bf16 v[46:49], v[158:161], v[236:239], v[46:49]
	v_mfma_f32_16x16x32_bf16 v[42:45], v[138:141], v[244:247], v[42:45]
	v_mfma_f32_16x16x32_bf16 v[38:41], v[158:161], v[244:247], v[38:41]
	s_setprio 1
	s_setprio 0
	v_mfma_f32_16x16x32_bf16 v[34:37], v[178:181], v[216:219], v[34:37]
	v_mfma_f32_16x16x32_bf16 v[30:33], v[208:211], v[216:219], v[30:33]
	v_mfma_f32_16x16x32_bf16 v[26:29], v[178:181], v[224:227], v[26:29]
	v_mfma_f32_16x16x32_bf16 v[22:25], v[208:211], v[224:227], v[22:25]
	v_mfma_f32_16x16x32_bf16 v[18:21], v[178:181], v[232:235], v[18:21]
	v_mfma_f32_16x16x32_bf16 v[14:17], v[208:211], v[232:235], v[14:17]
	v_mfma_f32_16x16x32_bf16 v[10:13], v[178:181], v[240:243], v[10:13]
	v_mfma_f32_16x16x32_bf16 v[4:7], v[208:211], v[240:243], v[6:9]
	v_mfma_f32_16x16x32_bf16 v[34:37], v[204:207], v[220:223], v[34:37]
	v_mfma_f32_16x16x32_bf16 v[30:33], v[212:215], v[220:223], v[30:33]
	v_mfma_f32_16x16x32_bf16 v[26:29], v[204:207], v[228:231], v[26:29]
	v_mfma_f32_16x16x32_bf16 v[22:25], v[212:215], v[228:231], v[22:25]
	v_mfma_f32_16x16x32_bf16 v[18:21], v[204:207], v[236:239], v[18:21]
	v_mfma_f32_16x16x32_bf16 v[14:17], v[212:215], v[236:239], v[14:17]
	v_mfma_f32_16x16x32_bf16 v[10:13], v[204:207], v[244:247], v[10:13]
	v_mfma_f32_16x16x32_bf16 v[4:7], v[212:215], v[244:247], v[4:7]
	s_setprio 1
	s_barrier
; #define PG8_STAGE(bufoff, gbase, voff) do { _Pragma("unroll") for (int _i = 0; _i < 2; ++_i) \
;         __builtin_amdgcn_global_load_lds((const unsigned*)((const char*)(gbase) + (voff)[_i]), (PG8_LAS unsigned*)(lds + (bufoff) + ldsw + _i * 8192), 16, 0, 0); } while (0)
; #define PG8_LDA(dst, b, h) do { _Pragma("unroll") for (int m = 0; m < 4; ++m) _Pragma("unroll") for (int k = 0; k < 2; ++k) dst[m][k] = *(const PG8_LAS bf16x8*)(lds + PG8_SA(b, h) + aoff + m * 2048 + k * 1024); } while (0)
; #define PG8_LDB(dst, b, h) do { _Pragma("unroll") for (int n = 0; n < 2; ++n) _Pragma("unroll") for (int k = 0; k < 2; ++k) dst[n][k] = *(const PG8_LAS bf16x8*)(lds + PG8_SB(b, h) + boff + n * 2048 + k * 1024); } while (0)
; #define PG8_MMA(ai, bj, At, Bt) do { __builtin_amdgcn_s_setprio(1); _Pragma("unroll") for (int m = 0; m < 4; ++m) _Pragma("unroll") for (int n = 0; n < 2; ++n) _Pragma("unroll") for (int k = 0; k < 2; ++k) \
;         acc[ai][bj][m][n] = __builtin_amdgcn_mfma_f32_16x16x32_bf16(Bt[n][k], At[m][k], acc[ai][bj][m][n], 0, 0, 0); __builtin_amdgcn_s_setprio(0); } while (0)
; #define PG8_WAIT_V(n) asm volatile("s_waitcnt vmcnt(" #n ")" ::: "memory")
; #define PG8_WAIT_L(n) asm volatile("s_waitcnt lgkmcnt(" #n ")" ::: "memory")
; #define PG8_BAR __builtin_amdgcn_s_barrier()
; #define PG8_SCHED __builtin_amdgcn_sched_barrier(0)
; template <class Epi, class Sched, bool ALIGN_EPI = false, bool SP2 = false>
; __device__ __forceinline__ void gemm_phase(PG8_LAS unsigned char* lds, const Gemm g, const Sched& S, const Epi& E) {
;     ...
;             PG8_LDB(B0, 1, 0); PG8_LDB(B1, 1, 1); PG8_SCHED; PG8_LDA(At, 1, 0); PG8_STAGE(PG8_SA(0, 1), a2 + hstep, voffA);
;             PG8_WAIT_V(8); PG8_WAIT_L(0); PG8_BAR; PG8_MMA(0, 0, At, B0); PG8_MMA(0, 1, At, B1); PG8_BAR; PG8_SCHED;
;             PG8_LDA(At, 1, 1); PG8_STAGE(PG8_SB(1, 0), b3, voffB); PG8_STAGE(PG8_SB(1, 1), b3 + hstep, voffB); PG8_STAGE(PG8_SA(1, 0), a3, voffA);
;             PG8_WAIT_V(8); PG8_WAIT_L(0); PG8_BAR; PG8_MMA(1, 0, At, B0); PG8_MMA(1, 1, At, B1); PG8_BAR; PG8_SCHED;
	s_add_i32 s27, 0, 0x18000
	v_add_u32_e32 v2, s27, v173
	s_add_i32 s29, 0, 0x1c000
	ds_read_b128 v[134:137], v2
	ds_read_b128 v[138:141], v2 offset:1024
	ds_read_b128 v[154:157], v2 offset:2048
	ds_read_b128 v[158:161], v2 offset:3072
	v_add_u32_e32 v2, s29, v173
	ds_read_b128 v[178:181], v2
	ds_read_b128 v[204:207], v2 offset:1024
	ds_read_b128 v[208:211], v2 offset:2048
	ds_read_b128 v[212:215], v2 offset:3072
	s_add_u32 s100, s44, 0x80
	s_addc_u32 s101, s45, 0
	s_add_u32 s44, s44, 0x40000
	s_addc_u32 s45, s45, 0
	s_mov_b32 m0, s57
	ds_read_b128 v[216:219], v177 offset:32768
	ds_read_b128 v[220:223], v177 offset:33792
	ds_read_b128 v[224:227], v177 offset:34816
	ds_read_b128 v[228:231], v177 offset:35840
	ds_read_b128 v[232:235], v177 offset:36864
	ds_read_b128 v[236:239], v177 offset:37888
	ds_read_b128 v[240:243], v177 offset:38912
	ds_read_b128 v[244:247], v177 offset:39936
	global_load_lds_dwordx4 v142, s[44:45]
	s_mov_b32 m0, s58
	s_nop 0
	global_load_lds_dwordx4 v146, s[44:45]
	s_waitcnt vmcnt(8)
	s_waitcnt lgkmcnt(0)
	s_barrier
	s_setprio 0
	s_waitcnt lgkmcnt(0)
	v_mfma_f32_16x16x32_bf16 v[130:133], v[134:137], v[216:219], v[130:133]
	v_mfma_f32_16x16x32_bf16 v[126:129], v[154:157], v[216:219], v[126:129]
	v_mfma_f32_16x16x32_bf16 v[122:125], v[134:137], v[224:227], v[122:125]
	v_mfma_f32_16x16x32_bf16 v[118:121], v[154:157], v[224:227], v[118:121]
	v_mfma_f32_16x16x32_bf16 v[114:117], v[134:137], v[232:235], v[114:117]
	v_mfma_f32_16x16x32_bf16 v[110:113], v[154:157], v[232:235], v[110:113]
	v_mfma_f32_16x16x32_bf16 v[106:109], v[134:137], v[240:243], v[106:109]
	v_mfma_f32_16x16x32_bf16 v[102:105], v[154:157], v[240:243], v[102:105]
	v_mfma_f32_16x16x32_bf16 v[130:133], v[138:141], v[220:223], v[130:133]
	v_mfma_f32_16x16x32_bf16 v[126:129], v[158:161], v[220:223], v[126:129]
	v_mfma_f32_16x16x32_bf16 v[122:125], v[138:141], v[228:231], v[122:125]
	v_mfma_f32_16x16x32_bf16 v[118:121], v[158:161], v[228:231], v[118:121]
	v_mfma_f32_16x16x32_bf16 v[114:117], v[138:141], v[236:239], v[114:117]
	v_mfma_f32_16x16x32_bf16 v[110:113], v[158:161], v[236:239], v[110:113]
	v_mfma_f32_16x16x32_bf16 v[106:109], v[138:141], v[244:247], v[106:109]
	v_mfma_f32_16x16x32_bf16 v[102:105], v[158:161], v[244:247], v[102:105]
	s_setprio 1
	s_setprio 0
	v_mfma_f32_16x16x32_bf16 v[98:101], v[178:181], v[216:219], v[98:101]
	v_mfma_f32_16x16x32_bf16 v[94:97], v[208:211], v[216:219], v[94:97]
	v_mfma_f32_16x16x32_bf16 v[90:93], v[178:181], v[224:227], v[90:93]
	v_mfma_f32_16x16x32_bf16 v[86:89], v[208:211], v[224:227], v[86:89]
	v_mfma_f32_16x16x32_bf16 v[82:85], v[178:181], v[232:235], v[82:85]
	v_mfma_f32_16x16x32_bf16 v[78:81], v[208:211], v[232:235], v[78:81]
	v_mfma_f32_16x16x32_bf16 v[74:77], v[178:181], v[240:243], v[74:77]
	v_mfma_f32_16x16x32_bf16 v[70:73], v[208:211], v[240:243], v[70:73]
	v_mfma_f32_16x16x32_bf16 v[98:101], v[204:207], v[220:223], v[98:101]
	v_mfma_f32_16x16x32_bf16 v[94:97], v[212:215], v[220:223], v[94:97]
	v_mfma_f32_16x16x32_bf16 v[90:93], v[204:207], v[228:231], v[90:93]
	v_mfma_f32_16x16x32_bf16 v[86:89], v[212:215], v[228:231], v[86:89]
	v_mfma_f32_16x16x32_bf16 v[82:85], v[204:207], v[236:239], v[82:85]
	v_mfma_f32_16x16x32_bf16 v[78:81], v[212:215], v[236:239], v[78:81]
	v_mfma_f32_16x16x32_bf16 v[74:77], v[204:207], v[244:247], v[74:77]
	v_mfma_f32_16x16x32_bf16 v[70:73], v[212:215], v[244:247], v[70:73]
	s_setprio 1
	s_barrier
	s_add_i32 s27, s27, s54
	s_add_i32 m0, s27, 0xffffff80
	ds_read_b128 v[216:219], v177 offset:49152
	ds_read_b128 v[220:223], v177 offset:50176
	ds_read_b128 v[224:227], v177 offset:51200
	ds_read_b128 v[228:231], v177 offset:52224
	ds_read_b128 v[232:235], v177 offset:53248
	ds_read_b128 v[236:239], v177 offset:54272
	ds_read_b128 v[240:243], v177 offset:55296
	ds_read_b128 v[244:247], v177 offset:56320
	global_load_lds_dwordx4 v144, s[42:43] offset:128
	s_add_i32 m0, s27, 0x1f80
	s_add_i32 s27, s29, s54
	global_load_lds_dwordx4 v148, s[42:43] offset:128
	s_add_u32 s42, s42, 0x40080
	s_addc_u32 s43, s43, 0
	s_mov_b32 m0, s27
	s_nop 0
	global_load_lds_dwordx4 v144, s[42:43]
	s_add_i32 m0, s27, 0x2000
	s_nop 0
	global_load_lds_dwordx4 v148, s[42:43]
	s_mov_b32 m0, s61
	s_nop 0
	global_load_lds_dwordx4 v142, s[100:101]
	s_mov_b32 m0, s62
	s_nop 0
	global_load_lds_dwordx4 v146, s[100:101]
	s_nop 0
	s_waitcnt vmcnt(8)
	s_waitcnt lgkmcnt(0)
	s_barrier
	s_setprio 0
	s_waitcnt lgkmcnt(0)
	v_mfma_f32_16x16x32_bf16 v[66:69], v[134:137], v[216:219], v[66:69]
	v_mfma_f32_16x16x32_bf16 v[62:65], v[154:157], v[216:219], v[62:65]
	v_mfma_f32_16x16x32_bf16 v[58:61], v[134:137], v[224:227], v[58:61]
	v_mfma_f32_16x16x32_bf16 v[54:57], v[154:157], v[224:227], v[54:57]
	v_mfma_f32_16x16x32_bf16 v[50:53], v[134:137], v[232:235], v[50:53]
	v_mfma_f32_16x16x32_bf16 v[46:49], v[154:157], v[232:235], v[46:49]
	v_mfma_f32_16x16x32_bf16 v[42:45], v[134:137], v[240:243], v[42:45]
	v_mfma_f32_16x16x32_bf16 v[38:41], v[154:157], v[240:243], v[38:41]
	v_mfma_f32_16x16x32_bf16 v[66:69], v[138:141], v[220:223], v[66:69]
	v_mfma_f32_16x16x32_bf16 v[62:65], v[158:161], v[220:223], v[62:65]
	v_mfma_f32_16x16x32_bf16 v[58:61], v[138:141], v[228:231], v[58:61]
	v_mfma_f32_16x16x32_bf16 v[54:57], v[158:161], v[228:231], v[54:57]
	v_mfma_f32_16x16x32_bf16 v[50:53], v[138:141], v[236:239], v[50:53]
	v_mfma_f32_16x16x32_bf16 v[46:49], v[158:161], v[236:239], v[46:49]
	v_mfma_f32_16x16x32_bf16 v[42:45], v[138:141], v[244:247], v[42:45]
	v_mfma_f32_16x16x32_bf16 v[38:41], v[158:161], v[244:247], v[38:41]
	s_setprio 1
	s_setprio 0
	v_mfma_f32_16x16x32_bf16 v[34:37], v[178:181], v[216:219], v[34:37]
	v_mfma_f32_16x16x32_bf16 v[30:33], v[208:211], v[216:219], v[30:33]
	v_mfma_f32_16x16x32_bf16 v[26:29], v[178:181], v[224:227], v[26:29]
	v_mfma_f32_16x16x32_bf16 v[22:25], v[208:211], v[224:227], v[22:25]
	v_mfma_f32_16x16x32_bf16 v[18:21], v[178:181], v[232:235], v[18:21]
	v_mfma_f32_16x16x32_bf16 v[14:17], v[208:211], v[232:235], v[14:17]
	v_mfma_f32_16x16x32_bf16 v[8:11], v[178:181], v[240:243], v[10:13]
	v_mfma_f32_16x16x32_bf16 v[4:7], v[208:211], v[240:243], v[4:7]
	v_mfma_f32_16x16x32_bf16 v[34:37], v[204:207], v[220:223], v[34:37]
	v_mfma_f32_16x16x32_bf16 v[30:33], v[212:215], v[220:223], v[30:33]
	v_mfma_f32_16x16x32_bf16 v[26:29], v[204:207], v[228:231], v[26:29]
	v_mfma_f32_16x16x32_bf16 v[22:25], v[212:215], v[228:231], v[22:25]
	v_mfma_f32_16x16x32_bf16 v[18:21], v[204:207], v[236:239], v[18:21]
	v_mfma_f32_16x16x32_bf16 v[14:17], v[212:215], v[236:239], v[14:17]
	v_mfma_f32_16x16x32_bf16 v[10:13], v[204:207], v[244:247], v[8:11]
	v_mfma_f32_16x16x32_bf16 v[6:9], v[212:215], v[244:247], v[4:7]
	s_setprio 1
	s_barrier
	s_add_i32 s26, s26, 2
	s_add_u32 s40, s40, 0x100
	s_addc_u32 s41, s41, 0
	s_add_u32 s11, s11, 0x100
	s_addc_u32 s13, s13, 0
	s_cmp_gt_u32 s26, 13
	s_cbranch_scc0 .LBB0_2096
	s_and_b64 vcc, exec, s[8:9]
	s_cbranch_vccz .LBB0_2099
	s_barrier

; #define PG8_STAGE(bufoff, gbase, voff) do { _Pragma("unroll") for (int _i = 0; _i < 2; ++_i) \
;         __builtin_amdgcn_global_load_lds((const unsigned*)((const char*)(gbase) + (voff)[_i]), (PG8_LAS unsigned*)(lds + (bufoff) + ldsw + _i * 8192), 16, 0, 0); } while (0)
; #define PG8_LDA(dst, b, h) do { _Pragma("unroll") for (int m = 0; m < 4; ++m) _Pragma("unroll") for (int k = 0; k < 2; ++k) dst[m][k] = *(const PG8_LAS bf16x8*)(lds + PG8_SA(b, h) + aoff + m * 2048 + k * 1024); } while (0)
; #define PG8_LDB(dst, b, h) do { _Pragma("unroll") for (int n = 0; n < 2; ++n) _Pragma("unroll") for (int k = 0; k < 2; ++k) dst[n][k] = *(const PG8_LAS bf16x8*)(lds + PG8_SB(b, h) + boff + n * 2048 + k * 1024); } while (0)
; #define PG8_MMA(ai, bj, At, Bt) do { __builtin_amdgcn_s_setprio(1); _Pragma("unroll") for (int m = 0; m < 4; ++m) _Pragma("unroll") for (int n = 0; n < 2; ++n) _Pragma("unroll") for (int k = 0; k < 2; ++k) \
;         acc[ai][bj][m][n] = __builtin_amdgcn_mfma_f32_16x16x32_bf16(Bt[n][k], At[m][k], acc[ai][bj][m][n], 0, 0, 0); __builtin_amdgcn_s_setprio(0); } while (0)
; #define PG8_WAIT_V(n) asm volatile("s_waitcnt vmcnt(" #n ")" ::: "memory")
; #define PG8_WAIT_L(n) asm volatile("s_waitcnt lgkmcnt(" #n ")" ::: "memory")
; template <class Epi, class Sched, bool ALIGN_EPI = false, bool SP2 = false>
; __device__ __forceinline__ void gemm_phase(PG8_LAS unsigned char* lds, const Gemm g, const Sched& S, const Epi& E) {
;     ...
;             const bool last = (t == nt - 2);
;             const char* a1 = cA + (size_t)(t + 1) * kstep;
;             const char* a2 = last ? nA : cA + (size_t)(t + 2) * kstep; const char* b2 = last ? nB : cB + (size_t)(t + 2) * kstep;
;             const char* a3 = a2 + kstep; const char* b3 = b2 + kstep;
;             if (last && has_next) S.a_ready(nxt);
;             if constexpr (SP2) {
;             PG8_LDB(B0, 0, 0); PG8_LDB(B1, 0, 1); PG8_SCHED; PG8_LDA(At, 0, 0); PG8_STAGE(PG8_SA(1, 1), a1 + hstep, voffA);
;             PG8_WAIT_V(8); PG8_WAIT_L(0); PG8_BAR; PG8_MMA(0, 0, At, B0); PG8_MMA(0, 1, At, B1); PG8_BAR; PG8_SCHED;
;             PG8_LDA(At, 0, 1); PG8_STAGE(PG8_SB(0, 0), b2, voffB); PG8_STAGE(PG8_SB(0, 1), b2 + hstep, voffB); PG8_STAGE(PG8_SA(0, 0), a2, voffA);
;             PG8_WAIT_V(8); PG8_WAIT_L(0); PG8_BAR; PG8_MMA(1, 0, At, B0); PG8_MMA(1, 1, At, B1); PG8_BAR; PG8_SCHED;
.LBB0_2185:
	s_add_u32 s42, s40, 0x100
	s_addc_u32 s43, s41, 0
	s_add_i32 s37, 0, 0x10000
	s_cmp_eq_u32 s31, 28
	s_cselect_b32 s47, s5, s43
	s_cselect_b32 s46, s4, s42
	v_add_u32_e32 v135, s37, v173
	s_cselect_b32 s45, s35, s29
	s_cselect_b32 s44, s34, s2
	s_add_i32 s39, 0, 0x14000
	ds_read_b128 v[142:145], v135
	ds_read_b128 v[146:149], v135 offset:1024
	ds_read_b128 v[150:153], v135 offset:2048
	ds_read_b128 v[154:157], v135 offset:3072
	v_add_u32_e32 v135, s39, v173
	ds_read_b128 v[158:161], v135
	ds_read_b128 v[174:177], v135 offset:1024
	ds_read_b128 v[180:183], v135 offset:2048
	ds_read_b128 v[204:207], v135 offset:3072
	v_lshl_add_u64 v[162:163], s[40:41], 0, v[138:139]
	s_add_i32 m0, s55, 0xc000
	ds_read_b128 v[208:211], v179
	ds_read_b128 v[212:215], v179 offset:1024
	ds_read_b128 v[216:219], v179 offset:2048
	ds_read_b128 v[220:223], v179 offset:3072
	ds_read_b128 v[224:227], v179 offset:4096
	ds_read_b128 v[228:231], v179 offset:5120
	ds_read_b128 v[232:235], v179 offset:6144
	ds_read_b128 v[236:239], v179 offset:7168
	global_load_lds_dwordx4 v[162:163], off
	v_lshl_add_u64 v[162:163], s[40:41], 0, v[140:141]
	s_add_i32 m0, s55, 0xe000
	s_nop 0
	global_load_lds_dwordx4 v[162:163], off
	s_waitcnt vmcnt(8)
	s_waitcnt lgkmcnt(0)
	s_barrier
	s_setprio 0
	s_waitcnt lgkmcnt(0)
	v_mfma_f32_16x16x32_bf16 v[128:131], v[142:145], v[208:211], v[128:131]
	v_mfma_f32_16x16x32_bf16 v[124:127], v[150:153], v[208:211], v[124:127]
	v_mfma_f32_16x16x32_bf16 v[112:115], v[142:145], v[216:219], v[112:115]
	v_mfma_f32_16x16x32_bf16 v[108:111], v[150:153], v[216:219], v[108:111]
	v_mfma_f32_16x16x32_bf16 v[96:99], v[142:145], v[224:227], v[96:99]
	v_mfma_f32_16x16x32_bf16 v[92:95], v[150:153], v[224:227], v[92:95]
	v_mfma_f32_16x16x32_bf16 v[80:83], v[142:145], v[232:235], v[80:83]
	v_mfma_f32_16x16x32_bf16 v[76:79], v[150:153], v[232:235], v[76:79]
	v_mfma_f32_16x16x32_bf16 v[128:131], v[146:149], v[212:215], v[128:131]
	v_mfma_f32_16x16x32_bf16 v[124:127], v[154:157], v[212:215], v[124:127]
	v_mfma_f32_16x16x32_bf16 v[112:115], v[146:149], v[220:223], v[112:115]
	v_mfma_f32_16x16x32_bf16 v[108:111], v[154:157], v[220:223], v[108:111]
	v_mfma_f32_16x16x32_bf16 v[96:99], v[146:149], v[228:231], v[96:99]
	v_mfma_f32_16x16x32_bf16 v[92:95], v[154:157], v[228:231], v[92:95]
	v_mfma_f32_16x16x32_bf16 v[80:83], v[146:149], v[236:239], v[80:83]
	v_mfma_f32_16x16x32_bf16 v[76:79], v[154:157], v[236:239], v[76:79]
	s_setprio 1
	s_setprio 0
	v_mfma_f32_16x16x32_bf16 v[120:123], v[158:161], v[208:211], v[120:123]
	v_mfma_f32_16x16x32_bf16 v[116:119], v[180:183], v[208:211], v[116:119]
	v_mfma_f32_16x16x32_bf16 v[104:107], v[158:161], v[216:219], v[104:107]
	v_mfma_f32_16x16x32_bf16 v[100:103], v[180:183], v[216:219], v[100:103]
	v_mfma_f32_16x16x32_bf16 v[88:91], v[158:161], v[224:227], v[88:91]
	v_mfma_f32_16x16x32_bf16 v[84:87], v[180:183], v[224:227], v[84:87]
	v_mfma_f32_16x16x32_bf16 v[72:75], v[158:161], v[232:235], v[72:75]
	v_mfma_f32_16x16x32_bf16 v[68:71], v[180:183], v[232:235], v[68:71]
	v_mfma_f32_16x16x32_bf16 v[120:123], v[174:177], v[212:215], v[120:123]
	v_mfma_f32_16x16x32_bf16 v[116:119], v[204:207], v[212:215], v[116:119]
	v_mfma_f32_16x16x32_bf16 v[104:107], v[174:177], v[220:223], v[104:107]
	v_mfma_f32_16x16x32_bf16 v[100:103], v[204:207], v[220:223], v[100:103]
	v_mfma_f32_16x16x32_bf16 v[88:91], v[174:177], v[228:231], v[88:91]
	v_mfma_f32_16x16x32_bf16 v[84:87], v[204:207], v[228:231], v[84:87]
	v_mfma_f32_16x16x32_bf16 v[72:75], v[174:177], v[236:239], v[72:75]
	v_mfma_f32_16x16x32_bf16 v[68:71], v[204:207], v[236:239], v[68:71]
	s_setprio 1
	s_barrier
	s_add_i32 s37, s37, s54
	s_mov_b32 m0, s37
	ds_read_b128 v[208:211], v179 offset:16384
	ds_read_b128 v[212:215], v179 offset:17408
	ds_read_b128 v[216:219], v179 offset:18432
	ds_read_b128 v[220:223], v179 offset:19456
	ds_read_b128 v[224:227], v179 offset:20480
	ds_read_b128 v[228:231], v179 offset:21504
	ds_read_b128 v[232:235], v179 offset:22528
	ds_read_b128 v[236:239], v179 offset:23552
	global_load_lds_dwordx4 v2, s[44:45]
	s_add_i32 m0, s37, 0x2000
	s_add_u32 s40, s44, 0x80000
	s_addc_u32 s41, s45, 0
	s_add_i32 s37, s39, s54
	global_load_lds_dwordx4 v132, s[44:45]
	s_mov_b32 m0, s37
	s_nop 0
	global_load_lds_dwordx4 v2, s[40:41]
	s_add_i32 m0, s37, 0x2000
	s_nop 0
	global_load_lds_dwordx4 v132, s[40:41]
	s_mov_b32 m0, s55
	s_nop 0
	global_load_lds_dwordx4 v2, s[46:47]
	s_mov_b32 m0, s56
	s_nop 0
	global_load_lds_dwordx4 v132, s[46:47]
	s_waitcnt vmcnt(8)
	s_waitcnt lgkmcnt(0)
	s_barrier
; #define PG8_STAGE(bufoff, gbase, voff) do { _Pragma("unroll") for (int _i = 0; _i < 2; ++_i) \
;         __builtin_amdgcn_global_load_lds((const unsigned*)((const char*)(gbase) + (voff)[_i]), (PG8_LAS unsigned*)(lds + (bufoff) + ldsw + _i * 8192), 16, 0, 0); } while (0)
; #define PG8_LDA(dst, b, h) do { _Pragma("unroll") for (int m = 0; m < 4; ++m) _Pragma("unroll") for (int k = 0; k < 2; ++k) dst[m][k] = *(const PG8_LAS bf16x8*)(lds + PG8_SA(b, h) + aoff + m * 2048 + k * 1024); } while (0)
; #define PG8_LDB(dst, b, h) do { _Pragma("unroll") for (int n = 0; n < 2; ++n) _Pragma("unroll") for (int k = 0; k < 2; ++k) dst[n][k] = *(const PG8_LAS bf16x8*)(lds + PG8_SB(b, h) + boff + n * 2048 + k * 1024); } while (0)
; #define PG8_MMA(ai, bj, At, Bt) do { __builtin_amdgcn_s_setprio(1); _Pragma("unroll") for (int m = 0; m < 4; ++m) _Pragma("unroll") for (int n = 0; n < 2; ++n) _Pragma("unroll") for (int k = 0; k < 2; ++k) \
;         acc[ai][bj][m][n] = __builtin_amdgcn_mfma_f32_16x16x32_bf16(Bt[n][k], At[m][k], acc[ai][bj][m][n], 0, 0, 0); __builtin_amdgcn_s_setprio(0); } while (0)
; #define PG8_WAIT_V(n) asm volatile("s_waitcnt vmcnt(" #n ")" ::: "memory")
; #define PG8_WAIT_L(n) asm volatile("s_waitcnt lgkmcnt(" #n ")" ::: "memory")
; #define PG8_BAR __builtin_amdgcn_s_barrier()
; #define PG8_SCHED __builtin_amdgcn_sched_barrier(0)
; template <class Epi, class Sched, bool ALIGN_EPI = false, bool SP2 = false>
; __device__ __forceinline__ void gemm_phase(PG8_LAS unsigned char* lds, const Gemm g, const Sched& S, const Epi& E) {
;     ...
;             PG8_WAIT_V(8); PG8_WAIT_L(0); PG8_BAR; PG8_MMA(1, 0, At, B0); PG8_MMA(1, 1, At, B1); PG8_BAR; PG8_SCHED;
;             PG8_LDB(B0, 1, 0); PG8_LDB(B1, 1, 1); PG8_SCHED; PG8_LDA(At, 1, 0); PG8_STAGE(PG8_SA(0, 1), a2 + hstep, voffA);
;             PG8_WAIT_V(8); PG8_WAIT_L(0); PG8_BAR; PG8_MMA(0, 0, At, B0); PG8_MMA(0, 1, At, B1); PG8_BAR; PG8_SCHED;
	s_setprio 0
	s_waitcnt lgkmcnt(0)
	v_mfma_f32_16x16x32_bf16 v[64:67], v[142:145], v[208:211], v[64:67]
	v_mfma_f32_16x16x32_bf16 v[60:63], v[150:153], v[208:211], v[60:63]
	v_mfma_f32_16x16x32_bf16 v[48:51], v[142:145], v[216:219], v[48:51]
	v_mfma_f32_16x16x32_bf16 v[44:47], v[150:153], v[216:219], v[44:47]
	v_mfma_f32_16x16x32_bf16 v[32:35], v[142:145], v[224:227], v[32:35]
	v_mfma_f32_16x16x32_bf16 v[28:31], v[150:153], v[224:227], v[28:31]
	v_mfma_f32_16x16x32_bf16 v[16:19], v[142:145], v[232:235], v[16:19]
	v_mfma_f32_16x16x32_bf16 v[12:15], v[150:153], v[232:235], v[12:15]
	v_mfma_f32_16x16x32_bf16 v[64:67], v[146:149], v[212:215], v[64:67]
	v_mfma_f32_16x16x32_bf16 v[60:63], v[154:157], v[212:215], v[60:63]
	v_mfma_f32_16x16x32_bf16 v[48:51], v[146:149], v[220:223], v[48:51]
	v_mfma_f32_16x16x32_bf16 v[44:47], v[154:157], v[220:223], v[44:47]
	v_mfma_f32_16x16x32_bf16 v[32:35], v[146:149], v[228:231], v[32:35]
	v_mfma_f32_16x16x32_bf16 v[28:31], v[154:157], v[228:231], v[28:31]
	v_mfma_f32_16x16x32_bf16 v[16:19], v[146:149], v[236:239], v[16:19]
	v_mfma_f32_16x16x32_bf16 v[12:15], v[154:157], v[236:239], v[12:15]
	s_setprio 1
	s_setprio 0
	v_mfma_f32_16x16x32_bf16 v[56:59], v[158:161], v[208:211], v[56:59]
	v_mfma_f32_16x16x32_bf16 v[52:55], v[180:183], v[208:211], v[52:55]
	v_mfma_f32_16x16x32_bf16 v[40:43], v[158:161], v[216:219], v[40:43]
	v_mfma_f32_16x16x32_bf16 v[36:39], v[180:183], v[216:219], v[36:39]
	v_mfma_f32_16x16x32_bf16 v[24:27], v[158:161], v[224:227], v[24:27]
	v_mfma_f32_16x16x32_bf16 v[20:23], v[180:183], v[224:227], v[20:23]
	v_mfma_f32_16x16x32_bf16 v[8:11], v[158:161], v[232:235], v[8:11]
	v_mfma_f32_16x16x32_bf16 v[4:7], v[180:183], v[232:235], v[4:7]
	v_mfma_f32_16x16x32_bf16 v[56:59], v[174:177], v[212:215], v[56:59]
	v_mfma_f32_16x16x32_bf16 v[52:55], v[204:207], v[212:215], v[52:55]
	v_mfma_f32_16x16x32_bf16 v[40:43], v[174:177], v[220:223], v[40:43]
	v_mfma_f32_16x16x32_bf16 v[36:39], v[204:207], v[220:223], v[36:39]
	v_mfma_f32_16x16x32_bf16 v[24:27], v[174:177], v[228:231], v[24:27]
	v_mfma_f32_16x16x32_bf16 v[20:23], v[204:207], v[228:231], v[20:23]
	v_mfma_f32_16x16x32_bf16 v[8:11], v[174:177], v[236:239], v[8:11]
	v_mfma_f32_16x16x32_bf16 v[4:7], v[204:207], v[236:239], v[4:7]
	s_setprio 1
	s_barrier
	s_add_i32 s37, 0, 0x18000
	v_add_u32_e32 v135, s37, v173
	s_add_i32 s39, 0, 0x1c000
	ds_read_b128 v[142:145], v135
	ds_read_b128 v[146:149], v135 offset:1024
	ds_read_b128 v[150:153], v135 offset:2048
	ds_read_b128 v[154:157], v135 offset:3072
	v_add_u32_e32 v135, s39, v173
	ds_read_b128 v[158:161], v135
	ds_read_b128 v[174:177], v135 offset:1024
	ds_read_b128 v[180:183], v135 offset:2048
	ds_read_b128 v[204:207], v135 offset:3072
	s_add_u32 s40, s46, 0x80000
	s_addc_u32 s41, s47, 0
	s_mov_b32 m0, s57
	ds_read_b128 v[208:211], v179 offset:32768
	ds_read_b128 v[212:215], v179 offset:33792
	ds_read_b128 v[216:219], v179 offset:34816
	ds_read_b128 v[220:223], v179 offset:35840
	ds_read_b128 v[224:227], v179 offset:36864
	ds_read_b128 v[228:231], v179 offset:37888
	ds_read_b128 v[232:235], v179 offset:38912
	ds_read_b128 v[236:239], v179 offset:39936
	global_load_lds_dwordx4 v2, s[40:41]
	s_mov_b32 m0, s58
	s_nop 0
	global_load_lds_dwordx4 v132, s[40:41]
	s_nop 0
	s_waitcnt vmcnt(8)
	s_waitcnt lgkmcnt(0)
	s_barrier
	s_setprio 0
	s_waitcnt lgkmcnt(0)
	v_mfma_f32_16x16x32_bf16 v[128:131], v[142:145], v[208:211], v[128:131]
	v_mfma_f32_16x16x32_bf16 v[124:127], v[150:153], v[208:211], v[124:127]
	v_mfma_f32_16x16x32_bf16 v[112:115], v[142:145], v[216:219], v[112:115]
	v_mfma_f32_16x16x32_bf16 v[108:111], v[150:153], v[216:219], v[108:111]
	v_mfma_f32_16x16x32_bf16 v[96:99], v[142:145], v[224:227], v[96:99]
	v_mfma_f32_16x16x32_bf16 v[92:95], v[150:153], v[224:227], v[92:95]
	v_mfma_f32_16x16x32_bf16 v[80:83], v[142:145], v[232:235], v[80:83]
	v_mfma_f32_16x16x32_bf16 v[76:79], v[150:153], v[232:235], v[76:79]
	v_mfma_f32_16x16x32_bf16 v[128:131], v[146:149], v[212:215], v[128:131]
	v_mfma_f32_16x16x32_bf16 v[124:127], v[154:157], v[212:215], v[124:127]
	v_mfma_f32_16x16x32_bf16 v[112:115], v[146:149], v[220:223], v[112:115]
	v_mfma_f32_16x16x32_bf16 v[108:111], v[154:157], v[220:223], v[108:111]
	v_mfma_f32_16x16x32_bf16 v[96:99], v[146:149], v[228:231], v[96:99]
	v_mfma_f32_16x16x32_bf16 v[92:95], v[154:157], v[228:231], v[92:95]
	v_mfma_f32_16x16x32_bf16 v[80:83], v[146:149], v[236:239], v[80:83]
	v_mfma_f32_16x16x32_bf16 v[76:79], v[154:157], v[236:239], v[76:79]
	s_setprio 1
	s_setprio 0
	v_mfma_f32_16x16x32_bf16 v[120:123], v[158:161], v[208:211], v[120:123]
	v_mfma_f32_16x16x32_bf16 v[116:119], v[180:183], v[208:211], v[116:119]
	v_mfma_f32_16x16x32_bf16 v[104:107], v[158:161], v[216:219], v[104:107]
	v_mfma_f32_16x16x32_bf16 v[100:103], v[180:183], v[216:219], v[100:103]
	v_mfma_f32_16x16x32_bf16 v[88:91], v[158:161], v[224:227], v[88:91]
	v_mfma_f32_16x16x32_bf16 v[84:87], v[180:183], v[224:227], v[84:87]
	v_mfma_f32_16x16x32_bf16 v[72:75], v[158:161], v[232:235], v[72:75]
	v_mfma_f32_16x16x32_bf16 v[68:71], v[180:183], v[232:235], v[68:71]
	v_mfma_f32_16x16x32_bf16 v[120:123], v[174:177], v[212:215], v[120:123]
	v_mfma_f32_16x16x32_bf16 v[116:119], v[204:207], v[212:215], v[116:119]
	v_mfma_f32_16x16x32_bf16 v[104:107], v[174:177], v[220:223], v[104:107]
	v_mfma_f32_16x16x32_bf16 v[100:103], v[204:207], v[220:223], v[100:103]
	v_mfma_f32_16x16x32_bf16 v[88:91], v[174:177], v[228:231], v[88:91]
	v_mfma_f32_16x16x32_bf16 v[84:87], v[204:207], v[228:231], v[84:87]
	v_mfma_f32_16x16x32_bf16 v[72:75], v[174:177], v[236:239], v[72:75]
	v_mfma_f32_16x16x32_bf16 v[68:71], v[204:207], v[236:239], v[68:71]
	s_setprio 1
	s_barrier
; #define PG8_STAGE(bufoff, gbase, voff) do { _Pragma("unroll") for (int _i = 0; _i < 2; ++_i) \
;         __builtin_amdgcn_global_load_lds((const unsigned*)((const char*)(gbase) + (voff)[_i]), (PG8_LAS unsigned*)(lds + (bufoff) + ldsw + _i * 8192), 16, 0, 0); } while (0)
; #define PG8_LDA(dst, b, h) do { _Pragma("unroll") for (int m = 0; m < 4; ++m) _Pragma("unroll") for (int k = 0; k < 2; ++k) dst[m][k] = *(const PG8_LAS bf16x8*)(lds + PG8_SA(b, h) + aoff + m * 2048 + k * 1024); } while (0)
; #define PG8_MMA(ai, bj, At, Bt) do { __builtin_amdgcn_s_setprio(1); _Pragma("unroll") for (int m = 0; m < 4; ++m) _Pragma("unroll") for (int n = 0; n < 2; ++n) _Pragma("unroll") for (int k = 0; k < 2; ++k) \
;         acc[ai][bj][m][n] = __builtin_amdgcn_mfma_f32_16x16x32_bf16(Bt[n][k], At[m][k], acc[ai][bj][m][n], 0, 0, 0); __builtin_amdgcn_s_setprio(0); } while (0)
; #define PG8_WAIT_V(n) asm volatile("s_waitcnt vmcnt(" #n ")" ::: "memory")
; #define PG8_WAIT_L(n) asm volatile("s_waitcnt lgkmcnt(" #n ")" ::: "memory")
; #define PG8_BAR __builtin_amdgcn_s_barrier()
; #define PG8_SCHED __builtin_amdgcn_sched_barrier(0)
; template <class Epi, class Sched, bool ALIGN_EPI = false, bool SP2 = false>
; __device__ __forceinline__ void gemm_phase(PG8_LAS unsigned char* lds, const Gemm g, const Sched& S, const Epi& E) {
;     ...
;             PG8_LDA(At, 1, 1); PG8_STAGE(PG8_SB(1, 0), b3, voffB); PG8_STAGE(PG8_SB(1, 1), b3 + hstep, voffB); PG8_STAGE(PG8_SA(1, 0), a3, voffA);
;             PG8_WAIT_V(8); PG8_WAIT_L(0); PG8_BAR; PG8_MMA(1, 0, At, B0); PG8_MMA(1, 1, At, B1); PG8_BAR; PG8_SCHED;
	s_add_i32 s37, s37, s54
	s_add_i32 m0, s37, 0xffffff80
	ds_read_b128 v[208:211], v179 offset:49152
	ds_read_b128 v[212:215], v179 offset:50176
	ds_read_b128 v[216:219], v179 offset:51200
	ds_read_b128 v[220:223], v179 offset:52224
	ds_read_b128 v[224:227], v179 offset:53248
	ds_read_b128 v[228:231], v179 offset:54272
	ds_read_b128 v[232:235], v179 offset:55296
	ds_read_b128 v[236:239], v179 offset:56320
	global_load_lds_dwordx4 v2, s[44:45] offset:128
	s_add_i32 m0, s37, 0x1f80
	s_add_u32 s40, s44, 0x80080
	s_addc_u32 s41, s45, 0
	s_add_i32 s37, s39, s54
	global_load_lds_dwordx4 v132, s[44:45] offset:128
	s_mov_b32 m0, s37
	s_nop 0
	global_load_lds_dwordx4 v2, s[40:41]
	s_add_i32 m0, s37, 0x2000
	s_nop 0
	global_load_lds_dwordx4 v132, s[40:41]
	s_add_i32 m0, s60, 0xffffff80
	s_nop 0
	global_load_lds_dwordx4 v2, s[46:47] offset:128
	s_add_i32 m0, s61, 0xffffff80
	s_nop 0
	global_load_lds_dwordx4 v132, s[46:47] offset:128
	s_nop 0
	s_waitcnt vmcnt(8)
	s_waitcnt lgkmcnt(0)
	s_barrier
	s_setprio 0
	s_waitcnt lgkmcnt(0)
	v_mfma_f32_16x16x32_bf16 v[64:67], v[142:145], v[208:211], v[64:67]
	v_mfma_f32_16x16x32_bf16 v[60:63], v[150:153], v[208:211], v[60:63]
	v_mfma_f32_16x16x32_bf16 v[48:51], v[142:145], v[216:219], v[48:51]
	v_mfma_f32_16x16x32_bf16 v[44:47], v[150:153], v[216:219], v[44:47]
	v_mfma_f32_16x16x32_bf16 v[32:35], v[142:145], v[224:227], v[32:35]
	v_mfma_f32_16x16x32_bf16 v[28:31], v[150:153], v[224:227], v[28:31]
	v_mfma_f32_16x16x32_bf16 v[16:19], v[142:145], v[232:235], v[16:19]
	v_mfma_f32_16x16x32_bf16 v[12:15], v[150:153], v[232:235], v[12:15]
	v_mfma_f32_16x16x32_bf16 v[64:67], v[146:149], v[212:215], v[64:67]
	v_mfma_f32_16x16x32_bf16 v[60:63], v[154:157], v[212:215], v[60:63]
	v_mfma_f32_16x16x32_bf16 v[48:51], v[146:149], v[220:223], v[48:51]
	v_mfma_f32_16x16x32_bf16 v[44:47], v[154:157], v[220:223], v[44:47]
	v_mfma_f32_16x16x32_bf16 v[32:35], v[146:149], v[228:231], v[32:35]
	v_mfma_f32_16x16x32_bf16 v[28:31], v[154:157], v[228:231], v[28:31]
	v_mfma_f32_16x16x32_bf16 v[16:19], v[146:149], v[236:239], v[16:19]
	v_mfma_f32_16x16x32_bf16 v[12:15], v[154:157], v[236:239], v[12:15]
	s_setprio 1
	s_setprio 0
	v_mfma_f32_16x16x32_bf16 v[56:59], v[158:161], v[208:211], v[56:59]
	v_mfma_f32_16x16x32_bf16 v[52:55], v[180:183], v[208:211], v[52:55]
	v_mfma_f32_16x16x32_bf16 v[40:43], v[158:161], v[216:219], v[40:43]
	v_mfma_f32_16x16x32_bf16 v[36:39], v[180:183], v[216:219], v[36:39]
	v_mfma_f32_16x16x32_bf16 v[24:27], v[158:161], v[224:227], v[24:27]
	v_mfma_f32_16x16x32_bf16 v[20:23], v[180:183], v[224:227], v[20:23]
	v_mfma_f32_16x16x32_bf16 v[8:11], v[158:161], v[232:235], v[8:11]
	v_mfma_f32_16x16x32_bf16 v[4:7], v[180:183], v[232:235], v[4:7]
	v_mfma_f32_16x16x32_bf16 v[56:59], v[174:177], v[212:215], v[56:59]
	v_mfma_f32_16x16x32_bf16 v[52:55], v[204:207], v[212:215], v[52:55]
	v_mfma_f32_16x16x32_bf16 v[40:43], v[174:177], v[220:223], v[40:43]
	v_mfma_f32_16x16x32_bf16 v[36:39], v[204:207], v[220:223], v[36:39]
	v_mfma_f32_16x16x32_bf16 v[24:27], v[174:177], v[228:231], v[24:27]
	v_mfma_f32_16x16x32_bf16 v[20:23], v[204:207], v[228:231], v[20:23]
	v_mfma_f32_16x16x32_bf16 v[8:11], v[174:177], v[236:239], v[8:11]
	v_mfma_f32_16x16x32_bf16 v[4:7], v[204:207], v[236:239], v[4:7]
	s_setprio 1
	s_barrier
	s_add_i32 s31, s31, 2
	s_add_u32 s2, s2, 0x100
	s_addc_u32 s29, s29, 0
	s_cmp_gt_u32 s31, 29
	s_mov_b64 s[40:41], s[42:43]
	s_cbranch_scc0 .LBB0_2185
	s_and_b64 vcc, exec, s[26:27]
	s_cbranch_vccz .LBB0_2188
	s_barrier
